# 256x256 K-loops of P1/P7/P5/P8 hand-scheduled (prefetched LDS frags, skewed tail, K-chunk rotation); scan store address strength-reduced
# speedup vs baseline: 1.0254x; 1.0254x over previous
; __device__ __forceinline__ void scan_unit(const Params& p, int l, int u, unsigned char* lds) {
;     ...
;         for (int c = 0; c < NCHUNK; ++c) {
;             const float* fbc = fb + (c % 3) * CHUNK * FSTR + 8 * (lane & 7);
;             const float* fbv = fb + (c % 3) * CHUNK * FSTR + 320 + 16 * wid + 2 * (lane >> 3);
;             bf16_t* yp = Y + ((size_t)b * TPB) * 512 + h * 64 + 16 * wid + 2 * (lane >> 3);
.LBB0_565:
	s_and_b64 vcc, exec, s[4:5]
	s_cbranch_vccz .LBB0_517
	s_and_b64 s[4:5], s[2:3], exec
	s_mov_b32 s4, 0x9c9b000
	s_cselect_b32 s4, s4, 0x375b000
	s_add_u32 s28, s21, s4
	s_addc_u32 s50, s31, 0
	s_lshl_b32 s4, s80, 4
	s_ashr_i32 s5, s4, 31
	s_mul_hi_i32 s51, s81, 0x240000
	s_mul_i32 s81, s81, 0x240000
	s_add_u32 s28, s28, s81
	s_addc_u32 s50, s50, s51
	s_lshl_b32 s39, s39, 7
	s_add_u32 s28, s28, s39
	s_addc_u32 s39, s50, 0
	s_lshl_b64 s[50:51], s[4:5], 1
	s_add_u32 s50, s28, s50
	v_lshlrev_b32_e32 v0, 3, v76
	s_addc_u32 s51, s39, s51
	s_lshl_b32 s5, s80, 6
	v_and_b32_e32 v40, 56, v0
	v_lshrrev_b32_e32 v0, 2, v76
	s_add_i32 s5, s5, 0
	v_and_b32_e32 v41, 14, v0
	v_and_b32_e32 v0, 56, v76
	s_addk_i32 s5, 0xb10
	v_lshlrev_b32_e32 v160, 1, v41
	v_add_u32_e32 v42, s5, v0
	v_and_b32_e32 v0, 7, v76
	v_mov_b32_e32 v22, 0
	s_mov_b32 s18, 0
	v_lshl_add_u64 v[20:21], s[50:51], 0, v[160:161]
	v_lshl_add_u32 v43, v0, 5, 0
	s_mov_b32 s5, -1
	s_mov_b32 s28, 0
	v_mov_b32_e32 v23, v22
	v_mov_b32_e32 v24, v22
	v_mov_b32_e32 v25, v22
	v_mov_b32_e32 v26, v22
	v_mov_b32_e32 v27, v22
	v_mov_b32_e32 v28, v22
	v_mov_b32_e32 v29, v22
	v_mov_b32_e32 v30, v22
	v_mov_b32_e32 v31, v22
	v_mov_b32_e32 v32, v22
	v_mov_b32_e32 v33, v22
	v_mov_b32_e32 v34, v22
	v_mov_b32_e32 v35, v22
	v_mov_b32_e32 v36, v22
	v_mov_b32_e32 v37, v22
	s_cmp_lg_u64 s[2:3], 0
	s_movk_i32 s78, 0x400
	s_cselect_b32 s78, s78, 0xfffffc00
	s_cselect_b32 s79, 0, -1
	s_cselect_b32 s76, 0, 0x3fc00
	s_mov_b32 s77, 0
	v_lshl_add_u64 v[20:21], v[20:21], 0, s[76:77]
	s_barrier

; __device__ __forceinline__ void scan_unit(const Params& p, int l, int u, unsigned char* lds) {
;     ...
; #pragma unroll 1
;             for (int sl = 0; sl < CHUNK; sl += 2) {
;                 SCAN_STEP(ha, hb, sl)
;                 SCAN_STEP(hb, ha, sl + 1)
;             }
.LBB0_568:
	s_waitcnt lgkmcnt(1)
	v_pk_fma_f32 v[78:79], v[22:23], v[4:5], 0 op_sel_hi:[1,1,0]
	v_pk_fma_f32 v[4:5], v[30:31], v[4:5], 0 op_sel_hi:[1,1,0]
	v_pk_fma_f32 v[78:79], v[24:25], v[6:7], v[78:79]
	v_pk_fma_f32 v[4:5], v[32:33], v[6:7], v[4:5]
	s_waitcnt lgkmcnt(0)
	v_pk_fma_f32 v[6:7], v[26:27], v[0:1], v[78:79]
	v_pk_fma_f32 v[0:1], v[34:35], v[0:1], v[4:5]
	v_pk_fma_f32 v[4:5], v[28:29], v[2:3], v[6:7]
	v_pk_fma_f32 v[0:1], v[36:37], v[2:3], v[0:1]
	v_add_f32_e32 v2, v4, v5
	v_add_u32_e32 v80, s50, v44
	v_add_f32_e32 v0, v0, v1
	v_add_f32_dpp v2, v2, v2 quad_perm:[1,0,3,2] row_mask:0xf bank_mask:0xf bound_ctrl:1
	ds_read_b128 v[46:49], v80 offset:256
	ds_read_b128 v[50:53], v80 offset:272
	ds_read_b128 v[54:57], v80 offset:512
	ds_read_b128 v[58:61], v80 offset:768
	ds_read_b128 v[62:65], v80 offset:1024
	ds_read_b128 v[66:69], v80 offset:528
	ds_read_b128 v[70:73], v80 offset:784
	ds_read_b128 v[74:77], v80 offset:1040
	v_add_f32_dpp v2, v2, v2 quad_perm:[2,3,0,1] row_mask:0xf bank_mask:0xf bound_ctrl:1
	v_add_f32_dpp v0, v0, v0 quad_perm:[1,0,3,2] row_mask:0xf bank_mask:0xf bound_ctrl:1
	s_waitcnt lgkmcnt(7)
	v_pk_mul_f32 v[4:5], v[22:23], v[46:47]
	v_add_f32_dpp v2, v2, v2 row_half_mirror row_mask:0xf bank_mask:0xf bound_ctrl:1
	v_add_f32_dpp v0, v0, v0 quad_perm:[2,3,0,1] row_mask:0xf bank_mask:0xf bound_ctrl:1
	s_waitcnt lgkmcnt(5)
	v_pk_fma_f32 v[4:5], v[54:55], v[2:3], v[4:5] op_sel_hi:[1,0,1] neg_lo:[0,1,0] neg_hi:[0,1,0]
	v_pk_mul_f32 v[24:25], v[24:25], v[48:49]
	v_add_f32_dpp v0, v0, v0 row_half_mirror row_mask:0xf bank_mask:0xf bound_ctrl:1
	s_waitcnt lgkmcnt(4)
	v_pk_fma_f32 v[22:23], v[58:59], v[38:39], v[4:5] op_sel_hi:[1,0,1]
	v_pk_mul_f32 v[4:5], v[30:31], v[46:47]
	v_pk_mul_f32 v[32:33], v[32:33], v[48:49]
	v_pk_fma_f32 v[4:5], v[54:55], v[0:1], v[4:5] op_sel_hi:[1,0,1] neg_lo:[0,1,0] neg_hi:[0,1,0]
	v_pk_mul_f32 v[26:27], v[26:27], v[50:51]
	v_pk_mul_f32 v[28:29], v[28:29], v[52:53]
	v_add_u32_e32 v8, s39, v45
	v_pk_fma_f32 v[30:31], v[58:59], v[38:39], v[4:5] op_sel:[0,1,0]
	v_pk_fma_f32 v[24:25], v[56:57], v[2:3], v[24:25] op_sel_hi:[1,0,1] neg_lo:[0,1,0] neg_hi:[0,1,0]
	v_pk_fma_f32 v[32:33], v[56:57], v[0:1], v[32:33] op_sel_hi:[1,0,1] neg_lo:[0,1,0] neg_hi:[0,1,0]
	s_waitcnt lgkmcnt(2)
	v_pk_fma_f32 v[26:27], v[66:67], v[2:3], v[26:27] op_sel_hi:[1,0,1] neg_lo:[0,1,0] neg_hi:[0,1,0]
	v_pk_mul_f32 v[34:35], v[34:35], v[50:51]
	v_pk_fma_f32 v[2:3], v[68:69], v[2:3], v[28:29] op_sel_hi:[1,0,1] neg_lo:[0,1,0] neg_hi:[0,1,0]
	ds_read_b128 v[16:19], v80 offset:1552
	ds_read_b128 v[12:15], v80 offset:1568
	ds_read2_b64 v[8:11], v8 offset1:194
	v_pk_fma_f32 v[4:5], v[22:23], v[62:63], 0 op_sel_hi:[1,1,0]
	v_pk_fma_f32 v[6:7], v[30:31], v[62:63], 0 op_sel_hi:[1,1,0]
	v_pk_fma_f32 v[24:25], v[60:61], v[38:39], v[24:25] op_sel_hi:[1,0,1]
	v_pk_fma_f32 v[32:33], v[60:61], v[38:39], v[32:33] op_sel:[0,1,0]
	v_pk_fma_f32 v[34:35], v[66:67], v[0:1], v[34:35] op_sel_hi:[1,0,1] neg_lo:[0,1,0] neg_hi:[0,1,0]
	s_waitcnt lgkmcnt(4)
	v_pk_fma_f32 v[28:29], v[72:73], v[38:39], v[2:3] op_sel_hi:[1,0,1]
	v_pk_mul_f32 v[2:3], v[36:37], v[52:53]
	v_pk_fma_f32 v[4:5], v[24:25], v[64:65], v[4:5]
	v_pk_fma_f32 v[6:7], v[32:33], v[64:65], v[6:7]
	v_pk_fma_f32 v[26:27], v[70:71], v[38:39], v[26:27] op_sel_hi:[1,0,1]
	v_pk_fma_f32 v[34:35], v[70:71], v[38:39], v[34:35] op_sel:[0,1,0]
	v_pk_fma_f32 v[0:1], v[68:69], v[0:1], v[2:3] op_sel_hi:[1,0,1] neg_lo:[0,1,0] neg_hi:[0,1,0]
	s_waitcnt lgkmcnt(3)
	v_pk_fma_f32 v[4:5], v[26:27], v[74:75], v[4:5]
	v_pk_fma_f32 v[6:7], v[34:35], v[74:75], v[6:7]
	v_pk_fma_f32 v[36:37], v[72:73], v[38:39], v[0:1] op_sel:[0,1,0]
	v_pk_fma_f32 v[0:1], v[28:29], v[76:77], v[4:5]
	v_pk_fma_f32 v[2:3], v[36:37], v[76:77], v[6:7]
	s_waitcnt lgkmcnt(2)
	v_pk_fma_f32 v[38:39], v[22:23], v[16:17], 0 op_sel_hi:[1,1,0]
	v_add_f32_e32 v0, v0, v1
	v_add_f32_e32 v1, v2, v3
	v_pk_fma_f32 v[16:17], v[30:31], v[16:17], 0 op_sel_hi:[1,1,0]
	v_pk_fma_f32 v[38:39], v[24:25], v[18:19], v[38:39]
	v_add_f32_dpp v0, v0, v0 quad_perm:[1,0,3,2] row_mask:0xf bank_mask:0xf bound_ctrl:1
	v_add_f32_dpp v1, v1, v1 quad_perm:[1,0,3,2] row_mask:0xf bank_mask:0xf bound_ctrl:1
	v_pk_fma_f32 v[16:17], v[32:33], v[18:19], v[16:17]
	s_waitcnt lgkmcnt(1)
; __device__ __forceinline__ void scan_unit(const Params& p, int l, int u, unsigned char* lds) {
;     ...
; #pragma unroll 1
;             for (int sl = 0; sl < CHUNK; sl += 2) {
;                 SCAN_STEP(ha, hb, sl)
;                 SCAN_STEP(hb, ha, sl + 1)
;             }
;             __syncthreads();
;         }
	v_pk_fma_f32 v[18:19], v[26:27], v[12:13], v[38:39]
	v_add_f32_dpp v0, v0, v0 quad_perm:[2,3,0,1] row_mask:0xf bank_mask:0xf bound_ctrl:1
	v_add_f32_dpp v1, v1, v1 quad_perm:[2,3,0,1] row_mask:0xf bank_mask:0xf bound_ctrl:1
	v_pk_fma_f32 v[12:13], v[34:35], v[12:13], v[16:17]
	v_pk_fma_f32 v[16:17], v[28:29], v[14:15], v[18:19]
	v_add_f32_dpp v0, v0, v0 row_half_mirror row_mask:0xf bank_mask:0xf bound_ctrl:1
	v_add_f32_dpp v1, v1, v1 row_half_mirror row_mask:0xf bank_mask:0xf bound_ctrl:1
	v_pk_fma_f32 v[12:13], v[36:37], v[14:15], v[12:13]
	v_add_f32_e32 v14, v16, v17
	v_cvt_pk_bf16_f32 v2, v0, v1
	global_store_dword v[20:21], v2, off
	v_lshl_add_u64 v[20:21], v[20:21], 0, s[78:79]
	v_add_f32_dpp v14, v14, v14 quad_perm:[1,0,3,2] row_mask:0xf bank_mask:0xf bound_ctrl:1
	v_add_f32_e32 v12, v12, v13
	ds_read_b128 v[46:49], v80 offset:1808
	ds_read_b128 v[50:53], v80 offset:2064
	ds_read_b128 v[54:57], v80 offset:2320
	ds_read_b128 v[58:61], v80 offset:2576
	ds_read_b128 v[62:65], v80 offset:1824
	ds_read_b128 v[66:69], v80 offset:2080
	ds_read_b128 v[70:73], v80 offset:2336
	ds_read_b128 v[74:77], v80 offset:2592
	ds_read_b128 v[4:7], v80 offset:3104
	ds_read_b128 v[0:3], v80 offset:3120
	v_add_f32_dpp v14, v14, v14 quad_perm:[2,3,0,1] row_mask:0xf bank_mask:0xf bound_ctrl:1
	v_add_f32_dpp v12, v12, v12 quad_perm:[1,0,3,2] row_mask:0xf bank_mask:0xf bound_ctrl:1
	s_waitcnt lgkmcnt(9)
	v_pk_mul_f32 v[16:17], v[22:23], v[46:47]
	v_add_f32_dpp v14, v14, v14 row_half_mirror row_mask:0xf bank_mask:0xf bound_ctrl:1
	v_add_f32_dpp v12, v12, v12 quad_perm:[2,3,0,1] row_mask:0xf bank_mask:0xf bound_ctrl:1
	s_waitcnt lgkmcnt(8)
	v_pk_fma_f32 v[16:17], v[50:51], v[14:15], v[16:17] op_sel_hi:[1,0,1] neg_lo:[0,1,0] neg_hi:[0,1,0]
	v_pk_mul_f32 v[24:25], v[24:25], v[48:49]
	v_add_f32_dpp v12, v12, v12 row_half_mirror row_mask:0xf bank_mask:0xf bound_ctrl:1
	s_waitcnt lgkmcnt(7)
	v_pk_fma_f32 v[22:23], v[54:55], v[8:9], v[16:17] op_sel_hi:[1,0,1]
	v_pk_mul_f32 v[16:17], v[30:31], v[46:47]
	v_pk_mul_f32 v[32:33], v[32:33], v[48:49]
	v_pk_fma_f32 v[16:17], v[50:51], v[12:13], v[16:17] op_sel_hi:[1,0,1] neg_lo:[0,1,0] neg_hi:[0,1,0]
	s_waitcnt lgkmcnt(5)
	v_pk_mul_f32 v[26:27], v[26:27], v[62:63]
	v_pk_mul_f32 v[28:29], v[28:29], v[64:65]
	v_pk_fma_f32 v[30:31], v[54:55], v[8:9], v[16:17] op_sel:[0,1,0]
	v_pk_fma_f32 v[24:25], v[52:53], v[14:15], v[24:25] op_sel_hi:[1,0,1] neg_lo:[0,1,0] neg_hi:[0,1,0]
	v_pk_fma_f32 v[32:33], v[52:53], v[12:13], v[32:33] op_sel_hi:[1,0,1] neg_lo:[0,1,0] neg_hi:[0,1,0]
	s_waitcnt lgkmcnt(4)
	v_pk_fma_f32 v[26:27], v[66:67], v[14:15], v[26:27] op_sel_hi:[1,0,1] neg_lo:[0,1,0] neg_hi:[0,1,0]
	v_pk_mul_f32 v[34:35], v[34:35], v[62:63]
	v_pk_fma_f32 v[14:15], v[68:69], v[14:15], v[28:29] op_sel_hi:[1,0,1] neg_lo:[0,1,0] neg_hi:[0,1,0]
	v_pk_fma_f32 v[16:17], v[22:23], v[58:59], 0 op_sel_hi:[1,1,0]
	v_pk_fma_f32 v[18:19], v[30:31], v[58:59], 0 op_sel_hi:[1,1,0]
	v_pk_fma_f32 v[24:25], v[56:57], v[8:9], v[24:25] op_sel_hi:[1,0,1]
	v_pk_fma_f32 v[32:33], v[56:57], v[8:9], v[32:33] op_sel:[0,1,0]
	v_pk_fma_f32 v[34:35], v[66:67], v[12:13], v[34:35] op_sel_hi:[1,0,1] neg_lo:[0,1,0] neg_hi:[0,1,0]
	s_waitcnt lgkmcnt(3)
	v_pk_fma_f32 v[28:29], v[72:73], v[8:9], v[14:15] op_sel_hi:[1,0,1]
	v_pk_mul_f32 v[14:15], v[36:37], v[64:65]
	v_pk_fma_f32 v[16:17], v[24:25], v[60:61], v[16:17]
	v_pk_fma_f32 v[18:19], v[32:33], v[60:61], v[18:19]
	v_pk_fma_f32 v[26:27], v[70:71], v[8:9], v[26:27] op_sel_hi:[1,0,1]
	v_pk_fma_f32 v[34:35], v[70:71], v[8:9], v[34:35] op_sel:[0,1,0]
	v_pk_fma_f32 v[12:13], v[68:69], v[12:13], v[14:15] op_sel_hi:[1,0,1] neg_lo:[0,1,0] neg_hi:[0,1,0]
	s_waitcnt lgkmcnt(2)
	v_pk_fma_f32 v[16:17], v[26:27], v[74:75], v[16:17]
	v_pk_fma_f32 v[18:19], v[34:35], v[74:75], v[18:19]
	v_pk_fma_f32 v[36:37], v[72:73], v[8:9], v[12:13] op_sel:[0,1,0]
	v_pk_fma_f32 v[8:9], v[28:29], v[76:77], v[16:17]
	v_pk_fma_f32 v[12:13], v[36:37], v[76:77], v[18:19]
	v_add_f32_e32 v8, v8, v9
	v_add_f32_e32 v9, v12, v13
	v_add_f32_dpp v8, v8, v8 quad_perm:[1,0,3,2] row_mask:0xf bank_mask:0xf bound_ctrl:1
	v_add_f32_dpp v9, v9, v9 quad_perm:[1,0,3,2] row_mask:0xf bank_mask:0xf bound_ctrl:1
	v_add_f32_dpp v8, v8, v8 quad_perm:[2,3,0,1] row_mask:0xf bank_mask:0xf bound_ctrl:1
	v_add_f32_dpp v9, v9, v9 quad_perm:[2,3,0,1] row_mask:0xf bank_mask:0xf bound_ctrl:1
	v_add_f32_dpp v8, v8, v8 row_half_mirror row_mask:0xf bank_mask:0xf bound_ctrl:1
	v_add_f32_dpp v9, v9, v9 row_half_mirror row_mask:0xf bank_mask:0xf bound_ctrl:1
	s_add_i32 s77, s76, 2
	s_addk_i32 s50, 0xc20
	v_cvt_pk_bf16_f32 v12, v8, v9
	v_add_u32_e32 v45, 0xc20, v45
	s_cmp_gt_u32 s76, 29
	s_mov_b32 s76, s77
	v_mov_b64_e32 v[38:39], v[10:11]
	global_store_dword v[20:21], v12, off
	v_lshl_add_u64 v[20:21], v[20:21], 0, s[78:79]
	s_cbranch_scc0 .LBB0_568
	s_add_i32 s28, s28, 1
	s_add_i32 s18, s18, 32
	s_sub_i32 s5, s5, 32
	v_add_u32_e32 v42, 0xc200, v42
	s_cmpk_eq_i32 s28, 8
	s_cselect_b32 s76, 0x240000, 0
	s_cmp_lg_u64 s[2:3], 0
	s_cselect_b32 s76, 0, s76
	s_mov_b32 s77, 0
	v_lshl_add_u64 v[20:21], v[20:21], 0, s[76:77]
	s_cmpk_eq_i32 s28, 0x48
	v_add_u32_e32 v43, 0xc200, v43
	s_waitcnt lgkmcnt(0)
	s_barrier
	s_cbranch_scc0 .LBB0_567
	s_branch .LBB0_517

; __device__ __forceinline__ void gemm_stream256(f32x4 (&acc)[8][4], const Seg& cur, const Seg& nxt, bool has_next, bool first, int& st, unsigned char* lds, int tid) {
;     ...
;     for (int kt = 0; kt < nk; ++kt) {
;         const int idx = kt + 1;
;         const bool incur = idx < nk, doi = incur || has_next;
;         if (!late && doi) { if (incur) issue(apc, bpc, cur.lda, cur.ldb, idx * 64, s0 ^ 1); else issue(apn, bpn, nxt.lda, nxt.ldb, 0, s0 ^ 1); }
;         const unsigned char* As = lds + s0 * STAGE;
;         const unsigned char* Bs = As + 256 * 128;
; #pragma unroll
;         for (int ks = 0; ks < 2; ++ks) {
;             if (ks == 1 && late && doi) { if (incur) issue(apc, bpc, cur.lda, cur.ldb, idx * 64, s0 ^ 1); else issue(apn, bpn, nxt.lda, nxt.ldb, 0, s0 ^ 1); }
;             bf16x8 af[8], bfr[4];
;             const int co = ((ks * 4 + fq) ^ sz) * 16;
; #pragma unroll
;             for (int m = 0; m < 8; ++m) af[m] = *(const bf16x8*)(As + (wr * 128 + m * 16 + fr) * 128 + co);
; #pragma unroll
;             for (int n = 0; n < 4; ++n) bfr[n] = *(const bf16x8*)(Bs + (wc * 64 + n * 16 + fr) * 128 + co);
; #pragma unroll
;             for (int m = 0; m < 8; ++m)
; #pragma unroll
;                 for (int n = 0; n < 4; ++n) acc[m][n] = __builtin_amdgcn_mfma_f32_16x16x32_bf16(bfr[n], af[m], acc[m][n], 0, 0, 0);
;         }
;         asm volatile("s_waitcnt vmcnt(0) lgkmcnt(0)" ::: "memory");
;         __builtin_amdgcn_s_barrier();
;         asm volatile("" ::: "memory");
;         s0 ^= 1;
;     }
.LBB0_800:
.LBB0_799:
	v_readlane_b32 s78, v253, 0
	s_lshr_b32 s6, s78, 3
	s_and_b32 s6, s6, 15
	s_lshl_b32 s6, s6, 7
	s_cmpk_eq_i32 s6, 0x780
	s_cselect_b32 s6, 0, s6
	s_mov_b32 s7, 0
	s_mov_b32 s31, 0
	s_lshl_b32 s28, s77, 16
	s_xor_b32 s38, s28, 0x10000
	s_add_i32 s38, s5, s38
	v_add3_u32 v179, s28, v176, v167
	v_add3_u32 v160, s28, v176, v166
	v_add3_u32 v251, s28, v177, v167
	v_add3_u32 v250, s28, v177, v166
	ds_read_b128 v[180:183], v179 offset:32768
	ds_read_b128 v[184:187], v179 offset:34816
	ds_read_b128 v[188:191], v179 offset:36864
	ds_read_b128 v[192:195], v179 offset:38912
	ds_read_b128 v[230:233], v160
	ds_read_b128 v[234:237], v160 offset:2048
	ds_read_b128 v[238:241], v160 offset:4096
	ds_read_b128 v[242:245], v160 offset:6144
	v_lshl_add_u64 v[128:129], v[134:135], 0, s[6:7]
	v_lshl_add_u64 v[130:131], v[132:133], 0, s[6:7]
	s_mov_b64 s[80:81], 0xd29b080
	v_lshl_add_u64 v[162:163], v[128:129], 0, s[80:81]
	s_mov_b32 m0, s38
	s_nop 0
	global_load_lds_dwordx4 v[162:163], off
	s_mov_b64 s[80:81], 0xd2bb080
	v_lshl_add_u64 v[164:165], v[128:129], 0, s[80:81]
	s_add_i32 m0, s38, 0x2000
	s_nop 0
	global_load_lds_dwordx4 v[164:165], off
	s_mov_b64 s[80:81], 0xd2db080
	v_lshl_add_u64 v[162:163], v[128:129], 0, s[80:81]
	s_add_i32 m0, s38, 0x4000
	s_nop 0
	global_load_lds_dwordx4 v[162:163], off
	s_mov_b64 s[80:81], 0xd2fb080
	v_lshl_add_u64 v[164:165], v[128:129], 0, s[80:81]
	s_add_i32 m0, s38, 0x6000
	s_nop 0
	global_load_lds_dwordx4 v[164:165], off
	ds_read_b128 v[214:217], v251 offset:32768
	ds_read_b128 v[218:221], v251 offset:34816
	ds_read_b128 v[222:225], v251 offset:36864
	ds_read_b128 v[226:229], v251 offset:38912
	s_waitcnt lgkmcnt(11)
	ds_read_b128 v[246:249], v160 offset:8192
	s_waitcnt lgkmcnt(11)
	ds_read_b128 v[196:199], v160 offset:10240
	s_waitcnt lgkmcnt(11)
	ds_read_b128 v[152:155], v160 offset:12288
	s_waitcnt lgkmcnt(11)
	ds_read_b128 v[156:159], v160 offset:14336
	s_waitcnt lgkmcnt(11)
	v_mfma_f32_16x16x32_bf16 v[124:127], v[180:183], v[230:233], v[124:127]
	v_mfma_f32_16x16x32_bf16 v[120:123], v[184:187], v[230:233], v[120:123]
	v_mfma_f32_16x16x32_bf16 v[116:119], v[188:191], v[230:233], v[116:119]
	v_mfma_f32_16x16x32_bf16 v[112:115], v[192:195], v[230:233], v[112:115]
	s_mov_b64 s[80:81], 0x1252080
	v_lshl_add_u64 v[162:163], v[130:131], 0, s[80:81]
	s_add_i32 m0, s38, 0x8000
	s_nop 0
	global_load_lds_dwordx4 v[162:163], off
	ds_read_b128 v[230:233], v250
	s_waitcnt lgkmcnt(11)
	v_mfma_f32_16x16x32_bf16 v[108:111], v[180:183], v[234:237], v[108:111]
	v_mfma_f32_16x16x32_bf16 v[104:107], v[184:187], v[234:237], v[104:107]
	v_mfma_f32_16x16x32_bf16 v[100:103], v[188:191], v[234:237], v[100:103]
	v_mfma_f32_16x16x32_bf16 v[96:99], v[192:195], v[234:237], v[96:99]
	s_mov_b64 s[80:81], 0x1272080
	v_lshl_add_u64 v[164:165], v[130:131], 0, s[80:81]
	s_add_i32 m0, s38, 0xa000
	s_nop 0
	global_load_lds_dwordx4 v[164:165], off
	ds_read_b128 v[234:237], v250 offset:2048
	s_waitcnt lgkmcnt(11)
	v_mfma_f32_16x16x32_bf16 v[92:95], v[180:183], v[238:241], v[92:95]
	v_mfma_f32_16x16x32_bf16 v[88:91], v[184:187], v[238:241], v[88:91]
	v_mfma_f32_16x16x32_bf16 v[84:87], v[188:191], v[238:241], v[84:87]
	v_mfma_f32_16x16x32_bf16 v[80:83], v[192:195], v[238:241], v[80:83]
	s_mov_b64 s[80:81], 0x1292080
	v_lshl_add_u64 v[162:163], v[130:131], 0, s[80:81]
	s_add_i32 m0, s38, 0xc000
	s_nop 0
	global_load_lds_dwordx4 v[162:163], off
	ds_read_b128 v[238:241], v250 offset:4096
	s_waitcnt lgkmcnt(11)
	v_mfma_f32_16x16x32_bf16 v[76:79], v[180:183], v[242:245], v[76:79]
	v_mfma_f32_16x16x32_bf16 v[72:75], v[184:187], v[242:245], v[72:75]
	v_mfma_f32_16x16x32_bf16 v[68:71], v[188:191], v[242:245], v[68:71]
	v_mfma_f32_16x16x32_bf16 v[64:67], v[192:195], v[242:245], v[64:67]
	s_mov_b64 s[80:81], 0x12b2080
	v_lshl_add_u64 v[164:165], v[130:131], 0, s[80:81]
	s_add_i32 m0, s38, 0xe000
	s_nop 0
	global_load_lds_dwordx4 v[164:165], off
	ds_read_b128 v[242:245], v250 offset:6144
	s_waitcnt lgkmcnt(7)
	v_mfma_f32_16x16x32_bf16 v[60:63], v[180:183], v[246:249], v[60:63]
	v_mfma_f32_16x16x32_bf16 v[56:59], v[184:187], v[246:249], v[56:59]
	v_mfma_f32_16x16x32_bf16 v[52:55], v[188:191], v[246:249], v[52:55]
	v_mfma_f32_16x16x32_bf16 v[48:51], v[192:195], v[246:249], v[48:51]
	ds_read_b128 v[246:249], v250 offset:8192
	s_waitcnt lgkmcnt(7)
	v_mfma_f32_16x16x32_bf16 v[44:47], v[180:183], v[196:199], v[44:47]
	v_mfma_f32_16x16x32_bf16 v[40:43], v[184:187], v[196:199], v[40:43]
	v_mfma_f32_16x16x32_bf16 v[36:39], v[188:191], v[196:199], v[36:39]
	v_mfma_f32_16x16x32_bf16 v[32:35], v[192:195], v[196:199], v[32:35]
	ds_read_b128 v[196:199], v250 offset:10240
	s_waitcnt lgkmcnt(7)
	v_mfma_f32_16x16x32_bf16 v[28:31], v[180:183], v[152:155], v[28:31]
	v_mfma_f32_16x16x32_bf16 v[24:27], v[184:187], v[152:155], v[24:27]
	v_mfma_f32_16x16x32_bf16 v[20:23], v[188:191], v[152:155], v[20:23]
	v_mfma_f32_16x16x32_bf16 v[16:19], v[192:195], v[152:155], v[16:19]
	ds_read_b128 v[152:155], v250 offset:12288
	s_waitcnt lgkmcnt(7)
	v_mfma_f32_16x16x32_bf16 v[12:15], v[180:183], v[156:159], v[12:15]
	v_mfma_f32_16x16x32_bf16 v[4:7], v[184:187], v[156:159], v[4:7]
	v_mfma_f32_16x16x32_bf16 v[0:3], v[188:191], v[156:159], v[0:3]
	v_mfma_f32_16x16x32_bf16 v[8:11], v[192:195], v[156:159], v[8:11]
	ds_read_b128 v[156:159], v250 offset:14336
	s_waitcnt lgkmcnt(7)
	v_mfma_f32_16x16x32_bf16 v[124:127], v[214:217], v[230:233], v[124:127]
	v_mfma_f32_16x16x32_bf16 v[120:123], v[218:221], v[230:233], v[120:123]
	v_mfma_f32_16x16x32_bf16 v[116:119], v[222:225], v[230:233], v[116:119]
	v_mfma_f32_16x16x32_bf16 v[112:115], v[226:229], v[230:233], v[112:115]
	s_waitcnt lgkmcnt(6)
	v_mfma_f32_16x16x32_bf16 v[108:111], v[214:217], v[234:237], v[108:111]
	v_mfma_f32_16x16x32_bf16 v[104:107], v[218:221], v[234:237], v[104:107]
	v_mfma_f32_16x16x32_bf16 v[100:103], v[222:225], v[234:237], v[100:103]
	v_mfma_f32_16x16x32_bf16 v[96:99], v[226:229], v[234:237], v[96:99]
	s_waitcnt lgkmcnt(5)
	v_mfma_f32_16x16x32_bf16 v[92:95], v[214:217], v[238:241], v[92:95]
	v_mfma_f32_16x16x32_bf16 v[88:91], v[218:221], v[238:241], v[88:91]
	v_mfma_f32_16x16x32_bf16 v[84:87], v[222:225], v[238:241], v[84:87]
	v_mfma_f32_16x16x32_bf16 v[80:83], v[226:229], v[238:241], v[80:83]
	s_waitcnt lgkmcnt(4)
	v_mfma_f32_16x16x32_bf16 v[76:79], v[214:217], v[242:245], v[76:79]
	v_mfma_f32_16x16x32_bf16 v[72:75], v[218:221], v[242:245], v[72:75]
	v_mfma_f32_16x16x32_bf16 v[68:71], v[222:225], v[242:245], v[68:71]
	v_mfma_f32_16x16x32_bf16 v[64:67], v[226:229], v[242:245], v[64:67]
	s_add_u32 s6, s6, 0x80
	s_cmpk_eq_i32 s6, 0x780
	s_cselect_b32 s6, 0, s6
	s_add_i32 s31, s31, 1
	s_xor_b32 s77, s77, 1
	s_waitcnt vmcnt(0) lgkmcnt(0)
	s_barrier
; __device__ __forceinline__ void gemm_stream256(f32x4 (&acc)[8][4], const Seg& cur, const Seg& nxt, bool has_next, bool first, int& st, unsigned char* lds, int tid) {
;     ...
;     for (int kt = 0; kt < nk; ++kt) {
;         const int idx = kt + 1;
;         const bool incur = idx < nk, doi = incur || has_next;
;         if (!late && doi) { if (incur) issue(apc, bpc, cur.lda, cur.ldb, idx * 64, s0 ^ 1); else issue(apn, bpn, nxt.lda, nxt.ldb, 0, s0 ^ 1); }
;         const unsigned char* As = lds + s0 * STAGE;
;         const unsigned char* Bs = As + 256 * 128;
; #pragma unroll
;         for (int ks = 0; ks < 2; ++ks) {
;             if (ks == 1 && late && doi) { if (incur) issue(apc, bpc, cur.lda, cur.ldb, idx * 64, s0 ^ 1); else issue(apn, bpn, nxt.lda, nxt.ldb, 0, s0 ^ 1); }
;             bf16x8 af[8], bfr[4];
;             const int co = ((ks * 4 + fq) ^ sz) * 16;
; #pragma unroll
;             for (int m = 0; m < 8; ++m) af[m] = *(const bf16x8*)(As + (wr * 128 + m * 16 + fr) * 128 + co);
; #pragma unroll
;             for (int n = 0; n < 4; ++n) bfr[n] = *(const bf16x8*)(Bs + (wc * 64 + n * 16 + fr) * 128 + co);
; #pragma unroll
;             for (int m = 0; m < 8; ++m)
; #pragma unroll
;                 for (int n = 0; n < 4; ++n) acc[m][n] = __builtin_amdgcn_mfma_f32_16x16x32_bf16(bfr[n], af[m], acc[m][n], 0, 0, 0);
;         }
;         asm volatile("s_waitcnt vmcnt(0) lgkmcnt(0)" ::: "memory");
;         __builtin_amdgcn_s_barrier();
;         asm volatile("" ::: "memory");
;         s0 ^= 1;
;     }
.Lp5_kloop:
	s_lshl_b32 s28, s77, 16
	s_xor_b32 s38, s28, 0x10000
	s_add_i32 s38, s5, s38
	v_add3_u32 v179, s28, v176, v167
	v_add3_u32 v160, s28, v176, v166
	v_add3_u32 v251, s28, v177, v167
	v_add3_u32 v250, s28, v177, v166
	ds_read_b128 v[180:183], v179 offset:32768
	ds_read_b128 v[184:187], v179 offset:34816
	ds_read_b128 v[188:191], v179 offset:36864
	ds_read_b128 v[192:195], v179 offset:38912
	ds_read_b128 v[230:233], v160
	ds_read_b128 v[234:237], v160 offset:2048
	ds_read_b128 v[238:241], v160 offset:4096
	ds_read_b128 v[242:245], v160 offset:6144
	v_lshl_add_u64 v[128:129], v[134:135], 0, s[6:7]
	v_lshl_add_u64 v[130:131], v[132:133], 0, s[6:7]
	v_mfma_f32_16x16x32_bf16 v[60:63], v[214:217], v[246:249], v[60:63]
	v_mfma_f32_16x16x32_bf16 v[56:59], v[218:221], v[246:249], v[56:59]
	v_mfma_f32_16x16x32_bf16 v[52:55], v[222:225], v[246:249], v[52:55]
	v_mfma_f32_16x16x32_bf16 v[48:51], v[226:229], v[246:249], v[48:51]
	s_mov_b64 s[80:81], 0xd29b080
	v_lshl_add_u64 v[162:163], v[128:129], 0, s[80:81]
	s_mov_b32 m0, s38
	s_nop 0
	global_load_lds_dwordx4 v[162:163], off
	v_mfma_f32_16x16x32_bf16 v[44:47], v[214:217], v[196:199], v[44:47]
	v_mfma_f32_16x16x32_bf16 v[40:43], v[218:221], v[196:199], v[40:43]
	v_mfma_f32_16x16x32_bf16 v[36:39], v[222:225], v[196:199], v[36:39]
	v_mfma_f32_16x16x32_bf16 v[32:35], v[226:229], v[196:199], v[32:35]
	s_mov_b64 s[80:81], 0xd2bb080
	v_lshl_add_u64 v[164:165], v[128:129], 0, s[80:81]
	s_add_i32 m0, s38, 0x2000
	s_nop 0
	global_load_lds_dwordx4 v[164:165], off
	v_mfma_f32_16x16x32_bf16 v[28:31], v[214:217], v[152:155], v[28:31]
	v_mfma_f32_16x16x32_bf16 v[24:27], v[218:221], v[152:155], v[24:27]
	v_mfma_f32_16x16x32_bf16 v[20:23], v[222:225], v[152:155], v[20:23]
	v_mfma_f32_16x16x32_bf16 v[16:19], v[226:229], v[152:155], v[16:19]
	s_mov_b64 s[80:81], 0xd2db080
	v_lshl_add_u64 v[162:163], v[128:129], 0, s[80:81]
	s_add_i32 m0, s38, 0x4000
	s_nop 0
	global_load_lds_dwordx4 v[162:163], off
	v_mfma_f32_16x16x32_bf16 v[12:15], v[214:217], v[156:159], v[12:15]
	v_mfma_f32_16x16x32_bf16 v[4:7], v[218:221], v[156:159], v[4:7]
	v_mfma_f32_16x16x32_bf16 v[0:3], v[222:225], v[156:159], v[0:3]
	v_mfma_f32_16x16x32_bf16 v[8:11], v[226:229], v[156:159], v[8:11]
	s_mov_b64 s[80:81], 0xd2fb080
	v_lshl_add_u64 v[164:165], v[128:129], 0, s[80:81]
	s_add_i32 m0, s38, 0x6000
	s_nop 0
	global_load_lds_dwordx4 v[164:165], off
	s_waitcnt lgkmcnt(0)
	ds_read_b128 v[214:217], v251 offset:32768
	ds_read_b128 v[218:221], v251 offset:34816
	ds_read_b128 v[222:225], v251 offset:36864
	ds_read_b128 v[226:229], v251 offset:38912
	ds_read_b128 v[246:249], v160 offset:8192
	ds_read_b128 v[196:199], v160 offset:10240
	ds_read_b128 v[152:155], v160 offset:12288
	ds_read_b128 v[156:159], v160 offset:14336
	v_mfma_f32_16x16x32_bf16 v[124:127], v[180:183], v[230:233], v[124:127]
	v_mfma_f32_16x16x32_bf16 v[120:123], v[184:187], v[230:233], v[120:123]
	v_mfma_f32_16x16x32_bf16 v[116:119], v[188:191], v[230:233], v[116:119]
	v_mfma_f32_16x16x32_bf16 v[112:115], v[192:195], v[230:233], v[112:115]
	s_mov_b64 s[80:81], 0x1252080
	v_lshl_add_u64 v[162:163], v[130:131], 0, s[80:81]
	s_add_i32 m0, s38, 0x8000
	s_nop 0
	global_load_lds_dwordx4 v[162:163], off
	ds_read_b128 v[230:233], v250
	v_mfma_f32_16x16x32_bf16 v[108:111], v[180:183], v[234:237], v[108:111]
	v_mfma_f32_16x16x32_bf16 v[104:107], v[184:187], v[234:237], v[104:107]
	v_mfma_f32_16x16x32_bf16 v[100:103], v[188:191], v[234:237], v[100:103]
	v_mfma_f32_16x16x32_bf16 v[96:99], v[192:195], v[234:237], v[96:99]
	s_mov_b64 s[80:81], 0x1272080
	v_lshl_add_u64 v[164:165], v[130:131], 0, s[80:81]
	s_add_i32 m0, s38, 0xa000
	s_nop 0
	global_load_lds_dwordx4 v[164:165], off
	ds_read_b128 v[234:237], v250 offset:2048
	v_mfma_f32_16x16x32_bf16 v[92:95], v[180:183], v[238:241], v[92:95]
	v_mfma_f32_16x16x32_bf16 v[88:91], v[184:187], v[238:241], v[88:91]
	v_mfma_f32_16x16x32_bf16 v[84:87], v[188:191], v[238:241], v[84:87]
	v_mfma_f32_16x16x32_bf16 v[80:83], v[192:195], v[238:241], v[80:83]
	s_mov_b64 s[80:81], 0x1292080
	v_lshl_add_u64 v[162:163], v[130:131], 0, s[80:81]
	s_add_i32 m0, s38, 0xc000
	s_nop 0
	global_load_lds_dwordx4 v[162:163], off
	ds_read_b128 v[238:241], v250 offset:4096
	v_mfma_f32_16x16x32_bf16 v[76:79], v[180:183], v[242:245], v[76:79]
	v_mfma_f32_16x16x32_bf16 v[72:75], v[184:187], v[242:245], v[72:75]
	v_mfma_f32_16x16x32_bf16 v[68:71], v[188:191], v[242:245], v[68:71]
	v_mfma_f32_16x16x32_bf16 v[64:67], v[192:195], v[242:245], v[64:67]
	s_mov_b64 s[80:81], 0x12b2080
	v_lshl_add_u64 v[164:165], v[130:131], 0, s[80:81]
	s_add_i32 m0, s38, 0xe000
	s_nop 0
	global_load_lds_dwordx4 v[164:165], off
	ds_read_b128 v[242:245], v250 offset:6144
	s_waitcnt lgkmcnt(7)
	v_mfma_f32_16x16x32_bf16 v[60:63], v[180:183], v[246:249], v[60:63]
	v_mfma_f32_16x16x32_bf16 v[56:59], v[184:187], v[246:249], v[56:59]
	v_mfma_f32_16x16x32_bf16 v[52:55], v[188:191], v[246:249], v[52:55]
	v_mfma_f32_16x16x32_bf16 v[48:51], v[192:195], v[246:249], v[48:51]
	ds_read_b128 v[246:249], v250 offset:8192
	s_waitcnt lgkmcnt(7)
	v_mfma_f32_16x16x32_bf16 v[44:47], v[180:183], v[196:199], v[44:47]
	v_mfma_f32_16x16x32_bf16 v[40:43], v[184:187], v[196:199], v[40:43]
	v_mfma_f32_16x16x32_bf16 v[36:39], v[188:191], v[196:199], v[36:39]
	v_mfma_f32_16x16x32_bf16 v[32:35], v[192:195], v[196:199], v[32:35]
	ds_read_b128 v[196:199], v250 offset:10240
	s_waitcnt lgkmcnt(7)
	v_mfma_f32_16x16x32_bf16 v[28:31], v[180:183], v[152:155], v[28:31]
	v_mfma_f32_16x16x32_bf16 v[24:27], v[184:187], v[152:155], v[24:27]
	v_mfma_f32_16x16x32_bf16 v[20:23], v[188:191], v[152:155], v[20:23]
	v_mfma_f32_16x16x32_bf16 v[16:19], v[192:195], v[152:155], v[16:19]
	ds_read_b128 v[152:155], v250 offset:12288
	s_waitcnt lgkmcnt(7)
; __device__ __forceinline__ void gemm_stream256(f32x4 (&acc)[8][4], const Seg& cur, const Seg& nxt, bool has_next, bool first, int& st, unsigned char* lds, int tid) {
;     ...
;     for (int kt = 0; kt < nk; ++kt) {
;         const int idx = kt + 1;
;         const bool incur = idx < nk, doi = incur || has_next;
;         if (!late && doi) { if (incur) issue(apc, bpc, cur.lda, cur.ldb, idx * 64, s0 ^ 1); else issue(apn, bpn, nxt.lda, nxt.ldb, 0, s0 ^ 1); }
;         const unsigned char* As = lds + s0 * STAGE;
;         const unsigned char* Bs = As + 256 * 128;
; #pragma unroll
;         for (int ks = 0; ks < 2; ++ks) {
;             if (ks == 1 && late && doi) { if (incur) issue(apc, bpc, cur.lda, cur.ldb, idx * 64, s0 ^ 1); else issue(apn, bpn, nxt.lda, nxt.ldb, 0, s0 ^ 1); }
;             bf16x8 af[8], bfr[4];
;             const int co = ((ks * 4 + fq) ^ sz) * 16;
; #pragma unroll
;             for (int m = 0; m < 8; ++m) af[m] = *(const bf16x8*)(As + (wr * 128 + m * 16 + fr) * 128 + co);
; #pragma unroll
;             for (int n = 0; n < 4; ++n) bfr[n] = *(const bf16x8*)(Bs + (wc * 64 + n * 16 + fr) * 128 + co);
; #pragma unroll
;             for (int m = 0; m < 8; ++m)
; #pragma unroll
;                 for (int n = 0; n < 4; ++n) acc[m][n] = __builtin_amdgcn_mfma_f32_16x16x32_bf16(bfr[n], af[m], acc[m][n], 0, 0, 0);
;         }
;         asm volatile("s_waitcnt vmcnt(0) lgkmcnt(0)" ::: "memory");
;         __builtin_amdgcn_s_barrier();
;         asm volatile("" ::: "memory");
;         s0 ^= 1;
;     }
	v_mfma_f32_16x16x32_bf16 v[12:15], v[180:183], v[156:159], v[12:15]
	v_mfma_f32_16x16x32_bf16 v[4:7], v[184:187], v[156:159], v[4:7]
	v_mfma_f32_16x16x32_bf16 v[0:3], v[188:191], v[156:159], v[0:3]
	v_mfma_f32_16x16x32_bf16 v[8:11], v[192:195], v[156:159], v[8:11]
	ds_read_b128 v[156:159], v250 offset:14336
	s_waitcnt lgkmcnt(7)
	v_mfma_f32_16x16x32_bf16 v[124:127], v[214:217], v[230:233], v[124:127]
	v_mfma_f32_16x16x32_bf16 v[120:123], v[218:221], v[230:233], v[120:123]
	v_mfma_f32_16x16x32_bf16 v[116:119], v[222:225], v[230:233], v[116:119]
	v_mfma_f32_16x16x32_bf16 v[112:115], v[226:229], v[230:233], v[112:115]
	s_waitcnt lgkmcnt(6)
	v_mfma_f32_16x16x32_bf16 v[108:111], v[214:217], v[234:237], v[108:111]
	v_mfma_f32_16x16x32_bf16 v[104:107], v[218:221], v[234:237], v[104:107]
	v_mfma_f32_16x16x32_bf16 v[100:103], v[222:225], v[234:237], v[100:103]
	v_mfma_f32_16x16x32_bf16 v[96:99], v[226:229], v[234:237], v[96:99]
	s_waitcnt lgkmcnt(5)
	v_mfma_f32_16x16x32_bf16 v[92:95], v[214:217], v[238:241], v[92:95]
	v_mfma_f32_16x16x32_bf16 v[88:91], v[218:221], v[238:241], v[88:91]
	v_mfma_f32_16x16x32_bf16 v[84:87], v[222:225], v[238:241], v[84:87]
	v_mfma_f32_16x16x32_bf16 v[80:83], v[226:229], v[238:241], v[80:83]
	s_waitcnt lgkmcnt(4)
	v_mfma_f32_16x16x32_bf16 v[76:79], v[214:217], v[242:245], v[76:79]
	v_mfma_f32_16x16x32_bf16 v[72:75], v[218:221], v[242:245], v[72:75]
	v_mfma_f32_16x16x32_bf16 v[68:71], v[222:225], v[242:245], v[68:71]
	v_mfma_f32_16x16x32_bf16 v[64:67], v[226:229], v[242:245], v[64:67]
	s_add_u32 s6, s6, 0x80
	s_cmpk_eq_i32 s6, 0x780
	s_cselect_b32 s6, 0, s6
	s_add_i32 s31, s31, 1
	s_xor_b32 s77, s77, 1
	s_waitcnt vmcnt(0) lgkmcnt(0)
	s_barrier
	s_cmpk_lg_i32 s31, 15
	s_cbranch_scc1 .Lp5_kloop
	s_lshl_b32 s28, s77, 16
	s_xor_b32 s38, s28, 0x10000
	s_add_i32 s38, s5, s38
	v_add3_u32 v179, s28, v176, v167
	v_add3_u32 v160, s28, v176, v166
	v_add3_u32 v251, s28, v177, v167
	v_add3_u32 v250, s28, v177, v166
	ds_read_b128 v[180:183], v179 offset:32768
	ds_read_b128 v[184:187], v179 offset:34816
	ds_read_b128 v[188:191], v179 offset:36864
	ds_read_b128 v[192:195], v179 offset:38912
	ds_read_b128 v[230:233], v160
	ds_read_b128 v[234:237], v160 offset:2048
	ds_read_b128 v[238:241], v160 offset:4096
	ds_read_b128 v[242:245], v160 offset:6144
	v_mfma_f32_16x16x32_bf16 v[60:63], v[214:217], v[246:249], v[60:63]
	v_mfma_f32_16x16x32_bf16 v[56:59], v[218:221], v[246:249], v[56:59]
	v_mfma_f32_16x16x32_bf16 v[52:55], v[222:225], v[246:249], v[52:55]
	v_mfma_f32_16x16x32_bf16 v[48:51], v[226:229], v[246:249], v[48:51]
	v_mfma_f32_16x16x32_bf16 v[44:47], v[214:217], v[196:199], v[44:47]
	v_mfma_f32_16x16x32_bf16 v[40:43], v[218:221], v[196:199], v[40:43]
	v_mfma_f32_16x16x32_bf16 v[36:39], v[222:225], v[196:199], v[36:39]
	v_mfma_f32_16x16x32_bf16 v[32:35], v[226:229], v[196:199], v[32:35]
	v_mfma_f32_16x16x32_bf16 v[28:31], v[214:217], v[152:155], v[28:31]
	v_mfma_f32_16x16x32_bf16 v[24:27], v[218:221], v[152:155], v[24:27]
	v_mfma_f32_16x16x32_bf16 v[20:23], v[222:225], v[152:155], v[20:23]
	v_mfma_f32_16x16x32_bf16 v[16:19], v[226:229], v[152:155], v[16:19]
	v_mfma_f32_16x16x32_bf16 v[12:15], v[214:217], v[156:159], v[12:15]
	v_mfma_f32_16x16x32_bf16 v[4:7], v[218:221], v[156:159], v[4:7]
	v_mfma_f32_16x16x32_bf16 v[0:3], v[222:225], v[156:159], v[0:3]
	v_mfma_f32_16x16x32_bf16 v[8:11], v[226:229], v[156:159], v[8:11]
	s_waitcnt lgkmcnt(0)
	ds_read_b128 v[214:217], v251 offset:32768
	ds_read_b128 v[218:221], v251 offset:34816
	ds_read_b128 v[222:225], v251 offset:36864
	ds_read_b128 v[226:229], v251 offset:38912
	ds_read_b128 v[246:249], v160 offset:8192
	ds_read_b128 v[196:199], v160 offset:10240
	ds_read_b128 v[152:155], v160 offset:12288
	ds_read_b128 v[156:159], v160 offset:14336
	v_mfma_f32_16x16x32_bf16 v[124:127], v[180:183], v[230:233], v[124:127]
	v_mfma_f32_16x16x32_bf16 v[120:123], v[184:187], v[230:233], v[120:123]
	v_mfma_f32_16x16x32_bf16 v[116:119], v[188:191], v[230:233], v[116:119]
	v_mfma_f32_16x16x32_bf16 v[112:115], v[192:195], v[230:233], v[112:115]
	ds_read_b128 v[230:233], v250
	v_mfma_f32_16x16x32_bf16 v[108:111], v[180:183], v[234:237], v[108:111]
	v_mfma_f32_16x16x32_bf16 v[104:107], v[184:187], v[234:237], v[104:107]
	v_mfma_f32_16x16x32_bf16 v[100:103], v[188:191], v[234:237], v[100:103]
	v_mfma_f32_16x16x32_bf16 v[96:99], v[192:195], v[234:237], v[96:99]
	ds_read_b128 v[234:237], v250 offset:2048
	v_mfma_f32_16x16x32_bf16 v[92:95], v[180:183], v[238:241], v[92:95]
	v_mfma_f32_16x16x32_bf16 v[88:91], v[184:187], v[238:241], v[88:91]
	v_mfma_f32_16x16x32_bf16 v[84:87], v[188:191], v[238:241], v[84:87]
	v_mfma_f32_16x16x32_bf16 v[80:83], v[192:195], v[238:241], v[80:83]
	ds_read_b128 v[238:241], v250 offset:4096
	v_mfma_f32_16x16x32_bf16 v[76:79], v[180:183], v[242:245], v[76:79]
	v_mfma_f32_16x16x32_bf16 v[72:75], v[184:187], v[242:245], v[72:75]
	v_mfma_f32_16x16x32_bf16 v[68:71], v[188:191], v[242:245], v[68:71]
	v_mfma_f32_16x16x32_bf16 v[64:67], v[192:195], v[242:245], v[64:67]
	ds_read_b128 v[242:245], v250 offset:6144
	s_waitcnt lgkmcnt(7)
; __device__ __forceinline__ void gemm_stream256(f32x4 (&acc)[8][4], const Seg& cur, const Seg& nxt, bool has_next, bool first, int& st, unsigned char* lds, int tid) {
;     ...
;     for (int kt = 0; kt < nk; ++kt) {
;         const int idx = kt + 1;
;         const bool incur = idx < nk, doi = incur || has_next;
;         if (!late && doi) { if (incur) issue(apc, bpc, cur.lda, cur.ldb, idx * 64, s0 ^ 1); else issue(apn, bpn, nxt.lda, nxt.ldb, 0, s0 ^ 1); }
;         const unsigned char* As = lds + s0 * STAGE;
;         const unsigned char* Bs = As + 256 * 128;
; #pragma unroll
;         for (int ks = 0; ks < 2; ++ks) {
;             if (ks == 1 && late && doi) { if (incur) issue(apc, bpc, cur.lda, cur.ldb, idx * 64, s0 ^ 1); else issue(apn, bpn, nxt.lda, nxt.ldb, 0, s0 ^ 1); }
;             bf16x8 af[8], bfr[4];
;             const int co = ((ks * 4 + fq) ^ sz) * 16;
; #pragma unroll
;             for (int m = 0; m < 8; ++m) af[m] = *(const bf16x8*)(As + (wr * 128 + m * 16 + fr) * 128 + co);
; #pragma unroll
;             for (int n = 0; n < 4; ++n) bfr[n] = *(const bf16x8*)(Bs + (wc * 64 + n * 16 + fr) * 128 + co);
; #pragma unroll
;             for (int m = 0; m < 8; ++m)
; #pragma unroll
;                 for (int n = 0; n < 4; ++n) acc[m][n] = __builtin_amdgcn_mfma_f32_16x16x32_bf16(bfr[n], af[m], acc[m][n], 0, 0, 0);
;         }
;         asm volatile("s_waitcnt vmcnt(0) lgkmcnt(0)" ::: "memory");
;         __builtin_amdgcn_s_barrier();
;         asm volatile("" ::: "memory");
;         s0 ^= 1;
;     }
	v_mfma_f32_16x16x32_bf16 v[60:63], v[180:183], v[246:249], v[60:63]
	v_mfma_f32_16x16x32_bf16 v[56:59], v[184:187], v[246:249], v[56:59]
	v_mfma_f32_16x16x32_bf16 v[52:55], v[188:191], v[246:249], v[52:55]
	v_mfma_f32_16x16x32_bf16 v[48:51], v[192:195], v[246:249], v[48:51]
	ds_read_b128 v[246:249], v250 offset:8192
	s_waitcnt lgkmcnt(7)
	v_mfma_f32_16x16x32_bf16 v[44:47], v[180:183], v[196:199], v[44:47]
	v_mfma_f32_16x16x32_bf16 v[40:43], v[184:187], v[196:199], v[40:43]
	v_mfma_f32_16x16x32_bf16 v[36:39], v[188:191], v[196:199], v[36:39]
	v_mfma_f32_16x16x32_bf16 v[32:35], v[192:195], v[196:199], v[32:35]
	ds_read_b128 v[196:199], v250 offset:10240
	s_waitcnt lgkmcnt(7)
	v_mfma_f32_16x16x32_bf16 v[28:31], v[180:183], v[152:155], v[28:31]
	v_mfma_f32_16x16x32_bf16 v[24:27], v[184:187], v[152:155], v[24:27]
	v_mfma_f32_16x16x32_bf16 v[20:23], v[188:191], v[152:155], v[20:23]
	v_mfma_f32_16x16x32_bf16 v[16:19], v[192:195], v[152:155], v[16:19]
	ds_read_b128 v[152:155], v250 offset:12288
	s_waitcnt lgkmcnt(7)
	v_mfma_f32_16x16x32_bf16 v[12:15], v[180:183], v[156:159], v[12:15]
	v_mfma_f32_16x16x32_bf16 v[4:7], v[184:187], v[156:159], v[4:7]
	v_mfma_f32_16x16x32_bf16 v[0:3], v[188:191], v[156:159], v[0:3]
	v_mfma_f32_16x16x32_bf16 v[8:11], v[192:195], v[156:159], v[8:11]
	ds_read_b128 v[156:159], v250 offset:14336
	s_waitcnt lgkmcnt(7)
	v_mfma_f32_16x16x32_bf16 v[124:127], v[214:217], v[230:233], v[124:127]
	v_mfma_f32_16x16x32_bf16 v[120:123], v[218:221], v[230:233], v[120:123]
	v_mfma_f32_16x16x32_bf16 v[116:119], v[222:225], v[230:233], v[116:119]
	v_mfma_f32_16x16x32_bf16 v[112:115], v[226:229], v[230:233], v[112:115]
	s_waitcnt lgkmcnt(6)
	v_mfma_f32_16x16x32_bf16 v[108:111], v[214:217], v[234:237], v[108:111]
	v_mfma_f32_16x16x32_bf16 v[104:107], v[218:221], v[234:237], v[104:107]
	v_mfma_f32_16x16x32_bf16 v[100:103], v[222:225], v[234:237], v[100:103]
	v_mfma_f32_16x16x32_bf16 v[96:99], v[226:229], v[234:237], v[96:99]
	s_waitcnt lgkmcnt(5)
	v_mfma_f32_16x16x32_bf16 v[92:95], v[214:217], v[238:241], v[92:95]
	v_mfma_f32_16x16x32_bf16 v[88:91], v[218:221], v[238:241], v[88:91]
	v_mfma_f32_16x16x32_bf16 v[84:87], v[222:225], v[238:241], v[84:87]
	v_mfma_f32_16x16x32_bf16 v[80:83], v[226:229], v[238:241], v[80:83]
	s_waitcnt lgkmcnt(4)
	v_mfma_f32_16x16x32_bf16 v[76:79], v[214:217], v[242:245], v[76:79]
	v_mfma_f32_16x16x32_bf16 v[72:75], v[218:221], v[242:245], v[72:75]
	v_mfma_f32_16x16x32_bf16 v[68:71], v[222:225], v[242:245], v[68:71]
	v_mfma_f32_16x16x32_bf16 v[64:67], v[226:229], v[242:245], v[64:67]
	s_waitcnt lgkmcnt(3)
	v_mfma_f32_16x16x32_bf16 v[60:63], v[214:217], v[246:249], v[60:63]
	v_mfma_f32_16x16x32_bf16 v[56:59], v[218:221], v[246:249], v[56:59]
	v_mfma_f32_16x16x32_bf16 v[52:55], v[222:225], v[246:249], v[52:55]
	v_mfma_f32_16x16x32_bf16 v[48:51], v[226:229], v[246:249], v[48:51]
	s_waitcnt lgkmcnt(2)
	v_mfma_f32_16x16x32_bf16 v[44:47], v[214:217], v[196:199], v[44:47]
	v_mfma_f32_16x16x32_bf16 v[40:43], v[218:221], v[196:199], v[40:43]
	v_mfma_f32_16x16x32_bf16 v[36:39], v[222:225], v[196:199], v[36:39]
	v_mfma_f32_16x16x32_bf16 v[32:35], v[226:229], v[196:199], v[32:35]
	s_waitcnt lgkmcnt(1)
	v_mfma_f32_16x16x32_bf16 v[28:31], v[214:217], v[152:155], v[28:31]
	v_mfma_f32_16x16x32_bf16 v[24:27], v[218:221], v[152:155], v[24:27]
	v_mfma_f32_16x16x32_bf16 v[20:23], v[222:225], v[152:155], v[20:23]
	v_mfma_f32_16x16x32_bf16 v[16:19], v[226:229], v[152:155], v[16:19]
	s_waitcnt lgkmcnt(0)
	v_mfma_f32_16x16x32_bf16 v[12:15], v[214:217], v[156:159], v[12:15]
	v_mfma_f32_16x16x32_bf16 v[4:7], v[218:221], v[156:159], v[4:7]
	v_mfma_f32_16x16x32_bf16 v[0:3], v[222:225], v[156:159], v[0:3]
	v_mfma_f32_16x16x32_bf16 v[8:11], v[226:229], v[156:159], v[8:11]
	s_waitcnt vmcnt(0) lgkmcnt(0)
	s_barrier

; __device__ __forceinline__ void gemm_stream256(f32x4 (&acc)[8][4], const Seg& cur, const Seg& nxt, bool has_next, bool first, int& st, unsigned char* lds, int tid) {
;     ...
;     for (int kt = 0; kt < nk; ++kt) {
;         const int idx = kt + 1;
;         const bool incur = idx < nk, doi = incur || has_next;
;         if (!late && doi) { if (incur) issue(apc, bpc, cur.lda, cur.ldb, idx * 64, s0 ^ 1); else issue(apn, bpn, nxt.lda, nxt.ldb, 0, s0 ^ 1); }
;         const unsigned char* As = lds + s0 * STAGE;
;         const unsigned char* Bs = As + 256 * 128;
; #pragma unroll
;         for (int ks = 0; ks < 2; ++ks) {
;             if (ks == 1 && late && doi) { if (incur) issue(apc, bpc, cur.lda, cur.ldb, idx * 64, s0 ^ 1); else issue(apn, bpn, nxt.lda, nxt.ldb, 0, s0 ^ 1); }
;             bf16x8 af[8], bfr[4];
;             const int co = ((ks * 4 + fq) ^ sz) * 16;
; #pragma unroll
;             for (int m = 0; m < 8; ++m) af[m] = *(const bf16x8*)(As + (wr * 128 + m * 16 + fr) * 128 + co);
; #pragma unroll
;             for (int n = 0; n < 4; ++n) bfr[n] = *(const bf16x8*)(Bs + (wc * 64 + n * 16 + fr) * 128 + co);
; #pragma unroll
;             for (int m = 0; m < 8; ++m)
; #pragma unroll
;                 for (int n = 0; n < 4; ++n) acc[m][n] = __builtin_amdgcn_mfma_f32_16x16x32_bf16(bfr[n], af[m], acc[m][n], 0, 0, 0);
;         }
;         asm volatile("s_waitcnt vmcnt(0) lgkmcnt(0)" ::: "memory");
;         __builtin_amdgcn_s_barrier();
;         asm volatile("" ::: "memory");
;         s0 ^= 1;
;     }
.LBB0_1030:
	s_lshr_b32 s86, s52, 3
	s_and_b32 s86, s86, 15
	s_lshl_b32 s86, s86, 7
	s_cmpk_eq_i32 s86, 0x780
	s_cselect_b32 s86, 0, s86
	s_mov_b32 s87, 0
	s_mov_b32 s75, 0
	s_lshl_b32 s54, s41, 16
	s_xor_b32 s57, s54, 0x10000
	s_add_i32 s56, s49, s57
	v_add3_u32 v160, s54, v187, v191
	v_add3_u32 v133, s54, v187, v190
	v_add3_u32 v251, s54, v188, v191
	v_add3_u32 v250, s54, v188, v190
	ds_read_b128 v[166:169], v160 offset:32768
	ds_read_b128 v[170:173], v160 offset:34816
	ds_read_b128 v[174:177], v160 offset:36864
	ds_read_b128 v[152:155], v160 offset:38912
	ds_read_b128 v[230:233], v133
	ds_read_b128 v[234:237], v133 offset:2048
	ds_read_b128 v[238:241], v133 offset:4096
	ds_read_b128 v[242:245], v133 offset:6144
	v_lshl_add_u64 v[128:129], v[136:137], 0, s[86:87]
	v_lshl_add_u64 v[130:131], v[138:139], 0, s[86:87]
	v_lshl_add_u64 v[148:149], v[128:129], 0, s[94:95]
	s_mov_b32 m0, s56
	s_nop 0
	global_load_lds_dwordx4 v[148:149], off
	v_lshl_add_u64 v[150:151], v[128:129], 0, s[14:15]
	s_add_i32 m0, s56, 0x2000
	s_nop 0
	global_load_lds_dwordx4 v[150:151], off
	v_lshl_add_u64 v[148:149], v[128:129], 0, s[96:97]
	s_add_i32 m0, s56, 0x4000
	s_nop 0
	global_load_lds_dwordx4 v[148:149], off
	v_lshl_add_u64 v[150:151], v[128:129], 0, s[12:13]
	s_add_i32 m0, s56, 0x6000
	s_nop 0
	global_load_lds_dwordx4 v[150:151], off
	ds_read_b128 v[214:217], v251 offset:32768
	ds_read_b128 v[218:221], v251 offset:34816
	ds_read_b128 v[222:225], v251 offset:36864
	ds_read_b128 v[226:229], v251 offset:38912
	s_waitcnt lgkmcnt(11)
	ds_read_b128 v[246:249], v133 offset:8192
	s_waitcnt lgkmcnt(11)
	ds_read_b128 v[156:159], v133 offset:10240
	s_waitcnt lgkmcnt(11)
	ds_read_b128 v[140:143], v133 offset:12288
	s_waitcnt lgkmcnt(11)
	ds_read_b128 v[144:147], v133 offset:14336
	s_waitcnt lgkmcnt(11)
	v_mfma_f32_16x16x32_bf16 v[124:127], v[166:169], v[230:233], v[124:127]
	v_mfma_f32_16x16x32_bf16 v[120:123], v[170:173], v[230:233], v[120:123]
	v_mfma_f32_16x16x32_bf16 v[116:119], v[174:177], v[230:233], v[116:119]
	v_mfma_f32_16x16x32_bf16 v[112:115], v[152:155], v[230:233], v[112:115]
	s_mov_b64 s[70:71], 0x1452080
	v_lshl_add_u64 v[148:149], v[130:131], 0, s[70:71]
	s_add_i32 m0, s56, 0x8000
	s_nop 0
	global_load_lds_dwordx4 v[148:149], off
	ds_read_b128 v[230:233], v250
	s_waitcnt lgkmcnt(11)
	v_mfma_f32_16x16x32_bf16 v[108:111], v[166:169], v[234:237], v[108:111]
	v_mfma_f32_16x16x32_bf16 v[104:107], v[170:173], v[234:237], v[104:107]
	v_mfma_f32_16x16x32_bf16 v[100:103], v[174:177], v[234:237], v[100:103]
	v_mfma_f32_16x16x32_bf16 v[96:99], v[152:155], v[234:237], v[96:99]
	s_mov_b64 s[70:71], 0x1472080
	v_lshl_add_u64 v[150:151], v[130:131], 0, s[70:71]
	s_add_i32 m0, s56, 0xa000
	s_nop 0
	global_load_lds_dwordx4 v[150:151], off
	ds_read_b128 v[234:237], v250 offset:2048
	s_waitcnt lgkmcnt(11)
	v_mfma_f32_16x16x32_bf16 v[92:95], v[166:169], v[238:241], v[92:95]
	v_mfma_f32_16x16x32_bf16 v[88:91], v[170:173], v[238:241], v[88:91]
	v_mfma_f32_16x16x32_bf16 v[84:87], v[174:177], v[238:241], v[84:87]
	v_mfma_f32_16x16x32_bf16 v[80:83], v[152:155], v[238:241], v[80:83]
	s_mov_b64 s[70:71], 0x1492080
	v_lshl_add_u64 v[148:149], v[130:131], 0, s[70:71]
	s_add_i32 m0, s56, 0xc000
	s_nop 0
	global_load_lds_dwordx4 v[148:149], off
	ds_read_b128 v[238:241], v250 offset:4096
	s_waitcnt lgkmcnt(11)
	v_mfma_f32_16x16x32_bf16 v[76:79], v[166:169], v[242:245], v[76:79]
	v_mfma_f32_16x16x32_bf16 v[72:75], v[170:173], v[242:245], v[72:75]
	v_mfma_f32_16x16x32_bf16 v[64:67], v[174:177], v[242:245], v[64:67]
	v_mfma_f32_16x16x32_bf16 v[60:63], v[152:155], v[242:245], v[60:63]
	s_mov_b64 s[70:71], 0x14b2080
	v_lshl_add_u64 v[150:151], v[130:131], 0, s[70:71]
	s_add_i32 m0, s56, 0xe000
	s_nop 0
	global_load_lds_dwordx4 v[150:151], off
	ds_read_b128 v[242:245], v250 offset:6144
	s_waitcnt lgkmcnt(7)
	v_mfma_f32_16x16x32_bf16 v[56:59], v[166:169], v[246:249], v[56:59]
	v_mfma_f32_16x16x32_bf16 v[52:55], v[170:173], v[246:249], v[52:55]
	v_mfma_f32_16x16x32_bf16 v[48:51], v[174:177], v[246:249], v[48:51]
	v_mfma_f32_16x16x32_bf16 v[44:47], v[152:155], v[246:249], v[44:47]
	ds_read_b128 v[246:249], v250 offset:8192
	s_waitcnt lgkmcnt(7)
	v_mfma_f32_16x16x32_bf16 v[40:43], v[166:169], v[156:159], v[40:43]
	v_mfma_f32_16x16x32_bf16 v[36:39], v[170:173], v[156:159], v[36:39]
	v_mfma_f32_16x16x32_bf16 v[32:35], v[174:177], v[156:159], v[32:35]
	v_mfma_f32_16x16x32_bf16 v[28:31], v[152:155], v[156:159], v[28:31]
	ds_read_b128 v[156:159], v250 offset:10240
	s_waitcnt lgkmcnt(7)
	v_mfma_f32_16x16x32_bf16 v[24:27], v[166:169], v[140:143], v[24:27]
	v_mfma_f32_16x16x32_bf16 v[20:23], v[170:173], v[140:143], v[20:23]
	v_mfma_f32_16x16x32_bf16 v[16:19], v[174:177], v[140:143], v[16:19]
	v_mfma_f32_16x16x32_bf16 v[12:15], v[152:155], v[140:143], v[12:15]
	ds_read_b128 v[140:143], v250 offset:12288
	s_waitcnt lgkmcnt(7)
	v_mfma_f32_16x16x32_bf16 v[8:11], v[166:169], v[144:147], v[8:11]
	v_mfma_f32_16x16x32_bf16 v[4:7], v[170:173], v[144:147], v[4:7]
	v_mfma_f32_16x16x32_bf16 v[0:3], v[174:177], v[144:147], v[0:3]
	v_mfma_f32_16x16x32_bf16 v[68:71], v[152:155], v[144:147], v[68:71]
	ds_read_b128 v[144:147], v250 offset:14336
	s_waitcnt lgkmcnt(7)
	v_mfma_f32_16x16x32_bf16 v[124:127], v[214:217], v[230:233], v[124:127]
	v_mfma_f32_16x16x32_bf16 v[120:123], v[218:221], v[230:233], v[120:123]
	v_mfma_f32_16x16x32_bf16 v[116:119], v[222:225], v[230:233], v[116:119]
	v_mfma_f32_16x16x32_bf16 v[112:115], v[226:229], v[230:233], v[112:115]
	s_waitcnt lgkmcnt(6)
	v_mfma_f32_16x16x32_bf16 v[108:111], v[214:217], v[234:237], v[108:111]
	v_mfma_f32_16x16x32_bf16 v[104:107], v[218:221], v[234:237], v[104:107]
	v_mfma_f32_16x16x32_bf16 v[100:103], v[222:225], v[234:237], v[100:103]
	v_mfma_f32_16x16x32_bf16 v[96:99], v[226:229], v[234:237], v[96:99]
	s_waitcnt lgkmcnt(5)
	v_mfma_f32_16x16x32_bf16 v[92:95], v[214:217], v[238:241], v[92:95]
	v_mfma_f32_16x16x32_bf16 v[88:91], v[218:221], v[238:241], v[88:91]
	v_mfma_f32_16x16x32_bf16 v[84:87], v[222:225], v[238:241], v[84:87]
	v_mfma_f32_16x16x32_bf16 v[80:83], v[226:229], v[238:241], v[80:83]
	s_waitcnt lgkmcnt(4)
	v_mfma_f32_16x16x32_bf16 v[76:79], v[214:217], v[242:245], v[76:79]
	v_mfma_f32_16x16x32_bf16 v[72:75], v[218:221], v[242:245], v[72:75]
	v_mfma_f32_16x16x32_bf16 v[64:67], v[222:225], v[242:245], v[64:67]
	v_mfma_f32_16x16x32_bf16 v[60:63], v[226:229], v[242:245], v[60:63]
	s_add_u32 s86, s86, 0x80
	s_cmpk_eq_i32 s86, 0x780
	s_cselect_b32 s86, 0, s86
	s_add_i32 s75, s75, 1
	s_xor_b32 s41, s41, 1
	s_waitcnt vmcnt(0) lgkmcnt(0)
	s_barrier
; __device__ __forceinline__ void gemm_stream256(f32x4 (&acc)[8][4], const Seg& cur, const Seg& nxt, bool has_next, bool first, int& st, unsigned char* lds, int tid) {
;     ...
;     for (int kt = 0; kt < nk; ++kt) {
;         const int idx = kt + 1;
;         const bool incur = idx < nk, doi = incur || has_next;
;         if (!late && doi) { if (incur) issue(apc, bpc, cur.lda, cur.ldb, idx * 64, s0 ^ 1); else issue(apn, bpn, nxt.lda, nxt.ldb, 0, s0 ^ 1); }
;         const unsigned char* As = lds + s0 * STAGE;
;         const unsigned char* Bs = As + 256 * 128;
; #pragma unroll
;         for (int ks = 0; ks < 2; ++ks) {
;             if (ks == 1 && late && doi) { if (incur) issue(apc, bpc, cur.lda, cur.ldb, idx * 64, s0 ^ 1); else issue(apn, bpn, nxt.lda, nxt.ldb, 0, s0 ^ 1); }
;             bf16x8 af[8], bfr[4];
;             const int co = ((ks * 4 + fq) ^ sz) * 16;
; #pragma unroll
;             for (int m = 0; m < 8; ++m) af[m] = *(const bf16x8*)(As + (wr * 128 + m * 16 + fr) * 128 + co);
; #pragma unroll
;             for (int n = 0; n < 4; ++n) bfr[n] = *(const bf16x8*)(Bs + (wc * 64 + n * 16 + fr) * 128 + co);
; #pragma unroll
;             for (int m = 0; m < 8; ++m)
; #pragma unroll
;                 for (int n = 0; n < 4; ++n) acc[m][n] = __builtin_amdgcn_mfma_f32_16x16x32_bf16(bfr[n], af[m], acc[m][n], 0, 0, 0);
;         }
;         asm volatile("s_waitcnt vmcnt(0) lgkmcnt(0)" ::: "memory");
;         __builtin_amdgcn_s_barrier();
;         asm volatile("" ::: "memory");
;         s0 ^= 1;
;     }
.Lp7_kloop:
	s_lshl_b32 s54, s41, 16
	s_xor_b32 s57, s54, 0x10000
	s_add_i32 s56, s49, s57
	v_add3_u32 v160, s54, v187, v191
	v_add3_u32 v133, s54, v187, v190
	v_add3_u32 v251, s54, v188, v191
	v_add3_u32 v250, s54, v188, v190
	ds_read_b128 v[166:169], v160 offset:32768
	ds_read_b128 v[170:173], v160 offset:34816
	ds_read_b128 v[174:177], v160 offset:36864
	ds_read_b128 v[152:155], v160 offset:38912
	ds_read_b128 v[230:233], v133
	ds_read_b128 v[234:237], v133 offset:2048
	ds_read_b128 v[238:241], v133 offset:4096
	ds_read_b128 v[242:245], v133 offset:6144
	v_lshl_add_u64 v[128:129], v[136:137], 0, s[86:87]
	v_lshl_add_u64 v[130:131], v[138:139], 0, s[86:87]
	v_mfma_f32_16x16x32_bf16 v[56:59], v[214:217], v[246:249], v[56:59]
	v_mfma_f32_16x16x32_bf16 v[52:55], v[218:221], v[246:249], v[52:55]
	v_mfma_f32_16x16x32_bf16 v[48:51], v[222:225], v[246:249], v[48:51]
	v_mfma_f32_16x16x32_bf16 v[44:47], v[226:229], v[246:249], v[44:47]
	v_lshl_add_u64 v[148:149], v[128:129], 0, s[94:95]
	s_mov_b32 m0, s56
	s_nop 0
	global_load_lds_dwordx4 v[148:149], off
	v_mfma_f32_16x16x32_bf16 v[40:43], v[214:217], v[156:159], v[40:43]
	v_mfma_f32_16x16x32_bf16 v[36:39], v[218:221], v[156:159], v[36:39]
	v_mfma_f32_16x16x32_bf16 v[32:35], v[222:225], v[156:159], v[32:35]
	v_mfma_f32_16x16x32_bf16 v[28:31], v[226:229], v[156:159], v[28:31]
	v_lshl_add_u64 v[150:151], v[128:129], 0, s[14:15]
	s_add_i32 m0, s56, 0x2000
	s_nop 0
	global_load_lds_dwordx4 v[150:151], off
	v_mfma_f32_16x16x32_bf16 v[24:27], v[214:217], v[140:143], v[24:27]
	v_mfma_f32_16x16x32_bf16 v[20:23], v[218:221], v[140:143], v[20:23]
	v_mfma_f32_16x16x32_bf16 v[16:19], v[222:225], v[140:143], v[16:19]
	v_mfma_f32_16x16x32_bf16 v[12:15], v[226:229], v[140:143], v[12:15]
	v_lshl_add_u64 v[148:149], v[128:129], 0, s[96:97]
	s_add_i32 m0, s56, 0x4000
	s_nop 0
	global_load_lds_dwordx4 v[148:149], off
	v_mfma_f32_16x16x32_bf16 v[8:11], v[214:217], v[144:147], v[8:11]
	v_mfma_f32_16x16x32_bf16 v[4:7], v[218:221], v[144:147], v[4:7]
	v_mfma_f32_16x16x32_bf16 v[0:3], v[222:225], v[144:147], v[0:3]
	v_mfma_f32_16x16x32_bf16 v[68:71], v[226:229], v[144:147], v[68:71]
	v_lshl_add_u64 v[150:151], v[128:129], 0, s[12:13]
	s_add_i32 m0, s56, 0x6000
	s_nop 0
	global_load_lds_dwordx4 v[150:151], off
	s_waitcnt lgkmcnt(0)
	ds_read_b128 v[214:217], v251 offset:32768
	ds_read_b128 v[218:221], v251 offset:34816
	ds_read_b128 v[222:225], v251 offset:36864
	ds_read_b128 v[226:229], v251 offset:38912
	ds_read_b128 v[246:249], v133 offset:8192
	ds_read_b128 v[156:159], v133 offset:10240
	ds_read_b128 v[140:143], v133 offset:12288
	ds_read_b128 v[144:147], v133 offset:14336
	v_mfma_f32_16x16x32_bf16 v[124:127], v[166:169], v[230:233], v[124:127]
	v_mfma_f32_16x16x32_bf16 v[120:123], v[170:173], v[230:233], v[120:123]
	v_mfma_f32_16x16x32_bf16 v[116:119], v[174:177], v[230:233], v[116:119]
	v_mfma_f32_16x16x32_bf16 v[112:115], v[152:155], v[230:233], v[112:115]
	s_mov_b64 s[70:71], 0x1452080
	v_lshl_add_u64 v[148:149], v[130:131], 0, s[70:71]
	s_add_i32 m0, s56, 0x8000
	s_nop 0
	global_load_lds_dwordx4 v[148:149], off
	ds_read_b128 v[230:233], v250
	v_mfma_f32_16x16x32_bf16 v[108:111], v[166:169], v[234:237], v[108:111]
	v_mfma_f32_16x16x32_bf16 v[104:107], v[170:173], v[234:237], v[104:107]
	v_mfma_f32_16x16x32_bf16 v[100:103], v[174:177], v[234:237], v[100:103]
	v_mfma_f32_16x16x32_bf16 v[96:99], v[152:155], v[234:237], v[96:99]
	s_mov_b64 s[70:71], 0x1472080
	v_lshl_add_u64 v[150:151], v[130:131], 0, s[70:71]
	s_add_i32 m0, s56, 0xa000
	s_nop 0
	global_load_lds_dwordx4 v[150:151], off
	ds_read_b128 v[234:237], v250 offset:2048
	v_mfma_f32_16x16x32_bf16 v[92:95], v[166:169], v[238:241], v[92:95]
	v_mfma_f32_16x16x32_bf16 v[88:91], v[170:173], v[238:241], v[88:91]
	v_mfma_f32_16x16x32_bf16 v[84:87], v[174:177], v[238:241], v[84:87]
	v_mfma_f32_16x16x32_bf16 v[80:83], v[152:155], v[238:241], v[80:83]
	s_mov_b64 s[70:71], 0x1492080
	v_lshl_add_u64 v[148:149], v[130:131], 0, s[70:71]
	s_add_i32 m0, s56, 0xc000
	s_nop 0
	global_load_lds_dwordx4 v[148:149], off
	ds_read_b128 v[238:241], v250 offset:4096
	v_mfma_f32_16x16x32_bf16 v[76:79], v[166:169], v[242:245], v[76:79]
	v_mfma_f32_16x16x32_bf16 v[72:75], v[170:173], v[242:245], v[72:75]
	v_mfma_f32_16x16x32_bf16 v[64:67], v[174:177], v[242:245], v[64:67]
	v_mfma_f32_16x16x32_bf16 v[60:63], v[152:155], v[242:245], v[60:63]
	s_mov_b64 s[70:71], 0x14b2080
	v_lshl_add_u64 v[150:151], v[130:131], 0, s[70:71]
	s_add_i32 m0, s56, 0xe000
	s_nop 0
	global_load_lds_dwordx4 v[150:151], off
	ds_read_b128 v[242:245], v250 offset:6144
	s_waitcnt lgkmcnt(7)
; __device__ __forceinline__ void gemm_stream256(f32x4 (&acc)[8][4], const Seg& cur, const Seg& nxt, bool has_next, bool first, int& st, unsigned char* lds, int tid) {
;     ...
;     for (int kt = 0; kt < nk; ++kt) {
;         const int idx = kt + 1;
;         const bool incur = idx < nk, doi = incur || has_next;
;         if (!late && doi) { if (incur) issue(apc, bpc, cur.lda, cur.ldb, idx * 64, s0 ^ 1); else issue(apn, bpn, nxt.lda, nxt.ldb, 0, s0 ^ 1); }
;         const unsigned char* As = lds + s0 * STAGE;
;         const unsigned char* Bs = As + 256 * 128;
; #pragma unroll
;         for (int ks = 0; ks < 2; ++ks) {
;             if (ks == 1 && late && doi) { if (incur) issue(apc, bpc, cur.lda, cur.ldb, idx * 64, s0 ^ 1); else issue(apn, bpn, nxt.lda, nxt.ldb, 0, s0 ^ 1); }
;             bf16x8 af[8], bfr[4];
;             const int co = ((ks * 4 + fq) ^ sz) * 16;
; #pragma unroll
;             for (int m = 0; m < 8; ++m) af[m] = *(const bf16x8*)(As + (wr * 128 + m * 16 + fr) * 128 + co);
; #pragma unroll
;             for (int n = 0; n < 4; ++n) bfr[n] = *(const bf16x8*)(Bs + (wc * 64 + n * 16 + fr) * 128 + co);
; #pragma unroll
;             for (int m = 0; m < 8; ++m)
; #pragma unroll
;                 for (int n = 0; n < 4; ++n) acc[m][n] = __builtin_amdgcn_mfma_f32_16x16x32_bf16(bfr[n], af[m], acc[m][n], 0, 0, 0);
;         }
;         asm volatile("s_waitcnt vmcnt(0) lgkmcnt(0)" ::: "memory");
;         __builtin_amdgcn_s_barrier();
;         asm volatile("" ::: "memory");
;         s0 ^= 1;
;     }
	v_mfma_f32_16x16x32_bf16 v[56:59], v[166:169], v[246:249], v[56:59]
	v_mfma_f32_16x16x32_bf16 v[52:55], v[170:173], v[246:249], v[52:55]
	v_mfma_f32_16x16x32_bf16 v[48:51], v[174:177], v[246:249], v[48:51]
	v_mfma_f32_16x16x32_bf16 v[44:47], v[152:155], v[246:249], v[44:47]
	ds_read_b128 v[246:249], v250 offset:8192
	s_waitcnt lgkmcnt(7)
	v_mfma_f32_16x16x32_bf16 v[40:43], v[166:169], v[156:159], v[40:43]
	v_mfma_f32_16x16x32_bf16 v[36:39], v[170:173], v[156:159], v[36:39]
	v_mfma_f32_16x16x32_bf16 v[32:35], v[174:177], v[156:159], v[32:35]
	v_mfma_f32_16x16x32_bf16 v[28:31], v[152:155], v[156:159], v[28:31]
	ds_read_b128 v[156:159], v250 offset:10240
	s_waitcnt lgkmcnt(7)
	v_mfma_f32_16x16x32_bf16 v[24:27], v[166:169], v[140:143], v[24:27]
	v_mfma_f32_16x16x32_bf16 v[20:23], v[170:173], v[140:143], v[20:23]
	v_mfma_f32_16x16x32_bf16 v[16:19], v[174:177], v[140:143], v[16:19]
	v_mfma_f32_16x16x32_bf16 v[12:15], v[152:155], v[140:143], v[12:15]
	ds_read_b128 v[140:143], v250 offset:12288
	s_waitcnt lgkmcnt(7)
	v_mfma_f32_16x16x32_bf16 v[8:11], v[166:169], v[144:147], v[8:11]
	v_mfma_f32_16x16x32_bf16 v[4:7], v[170:173], v[144:147], v[4:7]
	v_mfma_f32_16x16x32_bf16 v[0:3], v[174:177], v[144:147], v[0:3]
	v_mfma_f32_16x16x32_bf16 v[68:71], v[152:155], v[144:147], v[68:71]
	ds_read_b128 v[144:147], v250 offset:14336
	s_waitcnt lgkmcnt(7)
	v_mfma_f32_16x16x32_bf16 v[124:127], v[214:217], v[230:233], v[124:127]
	v_mfma_f32_16x16x32_bf16 v[120:123], v[218:221], v[230:233], v[120:123]
	v_mfma_f32_16x16x32_bf16 v[116:119], v[222:225], v[230:233], v[116:119]
	v_mfma_f32_16x16x32_bf16 v[112:115], v[226:229], v[230:233], v[112:115]
	s_waitcnt lgkmcnt(6)
	v_mfma_f32_16x16x32_bf16 v[108:111], v[214:217], v[234:237], v[108:111]
	v_mfma_f32_16x16x32_bf16 v[104:107], v[218:221], v[234:237], v[104:107]
	v_mfma_f32_16x16x32_bf16 v[100:103], v[222:225], v[234:237], v[100:103]
	v_mfma_f32_16x16x32_bf16 v[96:99], v[226:229], v[234:237], v[96:99]
	s_waitcnt lgkmcnt(5)
	v_mfma_f32_16x16x32_bf16 v[92:95], v[214:217], v[238:241], v[92:95]
	v_mfma_f32_16x16x32_bf16 v[88:91], v[218:221], v[238:241], v[88:91]
	v_mfma_f32_16x16x32_bf16 v[84:87], v[222:225], v[238:241], v[84:87]
	v_mfma_f32_16x16x32_bf16 v[80:83], v[226:229], v[238:241], v[80:83]
	s_waitcnt lgkmcnt(4)
	v_mfma_f32_16x16x32_bf16 v[76:79], v[214:217], v[242:245], v[76:79]
	v_mfma_f32_16x16x32_bf16 v[72:75], v[218:221], v[242:245], v[72:75]
	v_mfma_f32_16x16x32_bf16 v[64:67], v[222:225], v[242:245], v[64:67]
	v_mfma_f32_16x16x32_bf16 v[60:63], v[226:229], v[242:245], v[60:63]
	s_add_u32 s86, s86, 0x80
	s_cmpk_eq_i32 s86, 0x780
	s_cselect_b32 s86, 0, s86
	s_add_i32 s75, s75, 1
	s_xor_b32 s41, s41, 1
	s_waitcnt vmcnt(0) lgkmcnt(0)
	s_barrier
	s_cmpk_lg_i32 s75, 15
	s_cbranch_scc1 .Lp7_kloop
	v_mfma_f32_16x16x32_bf16 v[56:59], v[214:217], v[246:249], v[56:59]
	v_mfma_f32_16x16x32_bf16 v[52:55], v[218:221], v[246:249], v[52:55]
	v_mfma_f32_16x16x32_bf16 v[48:51], v[222:225], v[246:249], v[48:51]
	v_mfma_f32_16x16x32_bf16 v[44:47], v[226:229], v[246:249], v[44:47]
	v_mfma_f32_16x16x32_bf16 v[40:43], v[214:217], v[156:159], v[40:43]
	v_mfma_f32_16x16x32_bf16 v[36:39], v[218:221], v[156:159], v[36:39]
	v_mfma_f32_16x16x32_bf16 v[32:35], v[222:225], v[156:159], v[32:35]
	v_mfma_f32_16x16x32_bf16 v[28:31], v[226:229], v[156:159], v[28:31]
	v_mfma_f32_16x16x32_bf16 v[24:27], v[214:217], v[140:143], v[24:27]
	v_mfma_f32_16x16x32_bf16 v[20:23], v[218:221], v[140:143], v[20:23]
	v_mfma_f32_16x16x32_bf16 v[16:19], v[222:225], v[140:143], v[16:19]
	v_mfma_f32_16x16x32_bf16 v[12:15], v[226:229], v[140:143], v[12:15]
	v_mfma_f32_16x16x32_bf16 v[8:11], v[214:217], v[144:147], v[8:11]
	v_mfma_f32_16x16x32_bf16 v[4:7], v[218:221], v[144:147], v[4:7]
	v_mfma_f32_16x16x32_bf16 v[0:3], v[222:225], v[144:147], v[0:3]
	v_mfma_f32_16x16x32_bf16 v[68:71], v[226:229], v[144:147], v[68:71]
	s_mov_b32 s2, s41
	s_xor_b32 s41, s41, 1
	s_branch .LBB0_1041

; __device__ __forceinline__ void gemm_stream256(f32x4 (&acc)[8][4], const Seg& cur, const Seg& nxt, bool has_next, bool first, int& st, unsigned char* lds, int tid) {
;     ...
;     for (int kt = 0; kt < nk; ++kt) {
;         const int idx = kt + 1;
;         const bool incur = idx < nk, doi = incur || has_next;
;         if (!late && doi) { if (incur) issue(apc, bpc, cur.lda, cur.ldb, idx * 64, s0 ^ 1); else issue(apn, bpn, nxt.lda, nxt.ldb, 0, s0 ^ 1); }
;         const unsigned char* As = lds + s0 * STAGE;
;         const unsigned char* Bs = As + 256 * 128;
; #pragma unroll
;         for (int ks = 0; ks < 2; ++ks) {
;             if (ks == 1 && late && doi) { if (incur) issue(apc, bpc, cur.lda, cur.ldb, idx * 64, s0 ^ 1); else issue(apn, bpn, nxt.lda, nxt.ldb, 0, s0 ^ 1); }
;             bf16x8 af[8], bfr[4];
;             const int co = ((ks * 4 + fq) ^ sz) * 16;
; #pragma unroll
;             for (int m = 0; m < 8; ++m) af[m] = *(const bf16x8*)(As + (wr * 128 + m * 16 + fr) * 128 + co);
; #pragma unroll
;             for (int n = 0; n < 4; ++n) bfr[n] = *(const bf16x8*)(Bs + (wc * 64 + n * 16 + fr) * 128 + co);
; #pragma unroll
;             for (int m = 0; m < 8; ++m)
; #pragma unroll
;                 for (int n = 0; n < 4; ++n) acc[m][n] = __builtin_amdgcn_mfma_f32_16x16x32_bf16(bfr[n], af[m], acc[m][n], 0, 0, 0);
;         }
;         asm volatile("s_waitcnt vmcnt(0) lgkmcnt(0)" ::: "memory");
;         __builtin_amdgcn_s_barrier();
;         asm volatile("" ::: "memory");
;         s0 ^= 1;
;     }
.LBB0_1079:
.LBB0_1078:
	v_readlane_b32 s78, v253, 0
	s_lshr_b32 s86, s78, 3
	s_and_b32 s86, s86, 15
	s_lshl_b32 s86, s86, 7
	s_mov_b32 s87, 0
	s_mov_b32 s90, 0
	s_lshl_b32 s2, s75, 16
	s_xor_b32 s91, s2, 0x10000
	s_add_i32 s91, s71, s91
	v_add3_u32 v179, s2, v174, v178
	v_add3_u32 v160, s2, v174, v177
	v_add3_u32 v251, s2, v175, v178
	v_add3_u32 v250, s2, v175, v177
	ds_read_b128 v[180:183], v179 offset:32768
	ds_read_b128 v[184:187], v179 offset:34816
	ds_read_b128 v[188:191], v179 offset:36864
	ds_read_b128 v[192:195], v179 offset:38912
	ds_read_b128 v[230:233], v160
	ds_read_b128 v[234:237], v160 offset:2048
	ds_read_b128 v[238:241], v160 offset:4096
	ds_read_b128 v[242:245], v160 offset:6144
	v_lshl_add_u64 v[128:129], v[150:151], 0, s[86:87]
	v_lshl_add_u64 v[130:131], v[148:149], 0, s[86:87]
	s_mov_b64 s[80:81], 0x669b080
	v_lshl_add_u64 v[162:163], v[128:129], 0, s[80:81]
	s_mov_b32 m0, s91
	s_nop 0
	global_load_lds_dwordx4 v[162:163], off
	s_mov_b64 s[80:81], 0x66f3080
	v_lshl_add_u64 v[164:165], v[128:129], 0, s[80:81]
	s_add_i32 m0, s91, 0x2000
	s_nop 0
	global_load_lds_dwordx4 v[164:165], off
	s_mov_b64 s[80:81], 0x674b080
	v_lshl_add_u64 v[162:163], v[128:129], 0, s[80:81]
	s_add_i32 m0, s91, 0x4000
	s_nop 0
	global_load_lds_dwordx4 v[162:163], off
	s_mov_b64 s[80:81], 0x67a3080
	v_lshl_add_u64 v[164:165], v[128:129], 0, s[80:81]
	s_add_i32 m0, s91, 0x6000
	s_nop 0
	global_load_lds_dwordx4 v[164:165], off
	ds_read_b128 v[214:217], v251 offset:32768
	ds_read_b128 v[218:221], v251 offset:34816
	ds_read_b128 v[222:225], v251 offset:36864
	ds_read_b128 v[226:229], v251 offset:38912
	s_waitcnt lgkmcnt(11)
	ds_read_b128 v[246:249], v160 offset:8192
	s_waitcnt lgkmcnt(11)
	ds_read_b128 v[196:199], v160 offset:10240
	s_waitcnt lgkmcnt(11)
	ds_read_b128 v[152:155], v160 offset:12288
	s_waitcnt lgkmcnt(11)
	ds_read_b128 v[156:159], v160 offset:14336
	s_waitcnt lgkmcnt(11)
	v_mfma_f32_16x16x32_bf16 v[124:127], v[180:183], v[230:233], v[124:127]
	v_mfma_f32_16x16x32_bf16 v[120:123], v[184:187], v[230:233], v[120:123]
	v_mfma_f32_16x16x32_bf16 v[116:119], v[188:191], v[230:233], v[116:119]
	v_mfma_f32_16x16x32_bf16 v[112:115], v[192:195], v[230:233], v[112:115]
	s_mov_b64 s[80:81], 0x1f52080
	v_lshl_add_u64 v[162:163], v[130:131], 0, s[80:81]
	s_add_i32 m0, s91, 0x8000
	s_nop 0
	global_load_lds_dwordx4 v[162:163], off
	ds_read_b128 v[230:233], v250
	s_waitcnt lgkmcnt(11)
	v_mfma_f32_16x16x32_bf16 v[108:111], v[180:183], v[234:237], v[108:111]
	v_mfma_f32_16x16x32_bf16 v[104:107], v[184:187], v[234:237], v[104:107]
	v_mfma_f32_16x16x32_bf16 v[100:103], v[188:191], v[234:237], v[100:103]
	v_mfma_f32_16x16x32_bf16 v[96:99], v[192:195], v[234:237], v[96:99]
	s_mov_b64 s[80:81], 0x1faa080
	v_lshl_add_u64 v[164:165], v[130:131], 0, s[80:81]
	s_add_i32 m0, s91, 0xa000
	s_nop 0
	global_load_lds_dwordx4 v[164:165], off
	ds_read_b128 v[234:237], v250 offset:2048
	s_waitcnt lgkmcnt(11)
	v_mfma_f32_16x16x32_bf16 v[92:95], v[180:183], v[238:241], v[92:95]
	v_mfma_f32_16x16x32_bf16 v[88:91], v[184:187], v[238:241], v[88:91]
	v_mfma_f32_16x16x32_bf16 v[84:87], v[188:191], v[238:241], v[84:87]
	v_mfma_f32_16x16x32_bf16 v[80:83], v[192:195], v[238:241], v[80:83]
	s_mov_b64 s[80:81], 0x2002080
	v_lshl_add_u64 v[162:163], v[130:131], 0, s[80:81]
	s_add_i32 m0, s91, 0xc000
	s_nop 0
	global_load_lds_dwordx4 v[162:163], off
	ds_read_b128 v[238:241], v250 offset:4096
	s_waitcnt lgkmcnt(11)
	v_mfma_f32_16x16x32_bf16 v[76:79], v[180:183], v[242:245], v[76:79]
	v_mfma_f32_16x16x32_bf16 v[72:75], v[184:187], v[242:245], v[72:75]
	v_mfma_f32_16x16x32_bf16 v[68:71], v[188:191], v[242:245], v[68:71]
	v_mfma_f32_16x16x32_bf16 v[64:67], v[192:195], v[242:245], v[64:67]
	s_mov_b64 s[80:81], 0x205a080
	v_lshl_add_u64 v[164:165], v[130:131], 0, s[80:81]
	s_add_i32 m0, s91, 0xe000
	s_nop 0
	global_load_lds_dwordx4 v[164:165], off
	ds_read_b128 v[242:245], v250 offset:6144
	s_waitcnt lgkmcnt(7)
	v_mfma_f32_16x16x32_bf16 v[60:63], v[180:183], v[246:249], v[60:63]
	v_mfma_f32_16x16x32_bf16 v[56:59], v[184:187], v[246:249], v[56:59]
	v_mfma_f32_16x16x32_bf16 v[52:55], v[188:191], v[246:249], v[52:55]
	v_mfma_f32_16x16x32_bf16 v[48:51], v[192:195], v[246:249], v[48:51]
	ds_read_b128 v[246:249], v250 offset:8192
	s_waitcnt lgkmcnt(7)
	v_mfma_f32_16x16x32_bf16 v[44:47], v[180:183], v[196:199], v[44:47]
	v_mfma_f32_16x16x32_bf16 v[40:43], v[184:187], v[196:199], v[40:43]
	v_mfma_f32_16x16x32_bf16 v[36:39], v[188:191], v[196:199], v[36:39]
	v_mfma_f32_16x16x32_bf16 v[32:35], v[192:195], v[196:199], v[32:35]
	ds_read_b128 v[196:199], v250 offset:10240
	s_waitcnt lgkmcnt(7)
	v_mfma_f32_16x16x32_bf16 v[28:31], v[180:183], v[152:155], v[28:31]
	v_mfma_f32_16x16x32_bf16 v[24:27], v[184:187], v[152:155], v[24:27]
	v_mfma_f32_16x16x32_bf16 v[20:23], v[188:191], v[152:155], v[20:23]
	v_mfma_f32_16x16x32_bf16 v[16:19], v[192:195], v[152:155], v[16:19]
	ds_read_b128 v[152:155], v250 offset:12288
	s_waitcnt lgkmcnt(7)
	v_mfma_f32_16x16x32_bf16 v[12:15], v[180:183], v[156:159], v[12:15]
	v_mfma_f32_16x16x32_bf16 v[4:7], v[184:187], v[156:159], v[4:7]
	v_mfma_f32_16x16x32_bf16 v[0:3], v[188:191], v[156:159], v[0:3]
	v_mfma_f32_16x16x32_bf16 v[8:11], v[192:195], v[156:159], v[8:11]
	ds_read_b128 v[156:159], v250 offset:14336
	s_waitcnt lgkmcnt(7)
	v_mfma_f32_16x16x32_bf16 v[124:127], v[214:217], v[230:233], v[124:127]
	v_mfma_f32_16x16x32_bf16 v[120:123], v[218:221], v[230:233], v[120:123]
	v_mfma_f32_16x16x32_bf16 v[116:119], v[222:225], v[230:233], v[116:119]
	v_mfma_f32_16x16x32_bf16 v[112:115], v[226:229], v[230:233], v[112:115]
	s_waitcnt lgkmcnt(6)
	v_mfma_f32_16x16x32_bf16 v[108:111], v[214:217], v[234:237], v[108:111]
	v_mfma_f32_16x16x32_bf16 v[104:107], v[218:221], v[234:237], v[104:107]
	v_mfma_f32_16x16x32_bf16 v[100:103], v[222:225], v[234:237], v[100:103]
	v_mfma_f32_16x16x32_bf16 v[96:99], v[226:229], v[234:237], v[96:99]
	s_waitcnt lgkmcnt(5)
	v_mfma_f32_16x16x32_bf16 v[92:95], v[214:217], v[238:241], v[92:95]
	v_mfma_f32_16x16x32_bf16 v[88:91], v[218:221], v[238:241], v[88:91]
	v_mfma_f32_16x16x32_bf16 v[84:87], v[222:225], v[238:241], v[84:87]
	v_mfma_f32_16x16x32_bf16 v[80:83], v[226:229], v[238:241], v[80:83]
	s_waitcnt lgkmcnt(4)
	v_mfma_f32_16x16x32_bf16 v[76:79], v[214:217], v[242:245], v[76:79]
	v_mfma_f32_16x16x32_bf16 v[72:75], v[218:221], v[242:245], v[72:75]
	v_mfma_f32_16x16x32_bf16 v[68:71], v[222:225], v[242:245], v[68:71]
	v_mfma_f32_16x16x32_bf16 v[64:67], v[226:229], v[242:245], v[64:67]
	s_add_u32 s86, s86, 0x80
	s_cmpk_eq_i32 s86, 0x1580
	s_cselect_b32 s86, 0, s86
	s_add_i32 s90, s90, 1
	s_xor_b32 s75, s75, 1
	s_waitcnt vmcnt(0) lgkmcnt(0)
	s_barrier
; __device__ __forceinline__ void gemm_stream256(f32x4 (&acc)[8][4], const Seg& cur, const Seg& nxt, bool has_next, bool first, int& st, unsigned char* lds, int tid) {
;     ...
;     for (int kt = 0; kt < nk; ++kt) {
;         const int idx = kt + 1;
;         const bool incur = idx < nk, doi = incur || has_next;
;         if (!late && doi) { if (incur) issue(apc, bpc, cur.lda, cur.ldb, idx * 64, s0 ^ 1); else issue(apn, bpn, nxt.lda, nxt.ldb, 0, s0 ^ 1); }
;         const unsigned char* As = lds + s0 * STAGE;
;         const unsigned char* Bs = As + 256 * 128;
; #pragma unroll
;         for (int ks = 0; ks < 2; ++ks) {
;             if (ks == 1 && late && doi) { if (incur) issue(apc, bpc, cur.lda, cur.ldb, idx * 64, s0 ^ 1); else issue(apn, bpn, nxt.lda, nxt.ldb, 0, s0 ^ 1); }
;             bf16x8 af[8], bfr[4];
;             const int co = ((ks * 4 + fq) ^ sz) * 16;
; #pragma unroll
;             for (int m = 0; m < 8; ++m) af[m] = *(const bf16x8*)(As + (wr * 128 + m * 16 + fr) * 128 + co);
; #pragma unroll
;             for (int n = 0; n < 4; ++n) bfr[n] = *(const bf16x8*)(Bs + (wc * 64 + n * 16 + fr) * 128 + co);
; #pragma unroll
;             for (int m = 0; m < 8; ++m)
; #pragma unroll
;                 for (int n = 0; n < 4; ++n) acc[m][n] = __builtin_amdgcn_mfma_f32_16x16x32_bf16(bfr[n], af[m], acc[m][n], 0, 0, 0);
;         }
;         asm volatile("s_waitcnt vmcnt(0) lgkmcnt(0)" ::: "memory");
;         __builtin_amdgcn_s_barrier();
;         asm volatile("" ::: "memory");
;         s0 ^= 1;
;     }
.Lp8_kloop:
	s_lshl_b32 s2, s75, 16
	s_xor_b32 s91, s2, 0x10000
	s_add_i32 s91, s71, s91
	v_add3_u32 v179, s2, v174, v178
	v_add3_u32 v160, s2, v174, v177
	v_add3_u32 v251, s2, v175, v178
	v_add3_u32 v250, s2, v175, v177
	ds_read_b128 v[180:183], v179 offset:32768
	ds_read_b128 v[184:187], v179 offset:34816
	ds_read_b128 v[188:191], v179 offset:36864
	ds_read_b128 v[192:195], v179 offset:38912
	ds_read_b128 v[230:233], v160
	ds_read_b128 v[234:237], v160 offset:2048
	ds_read_b128 v[238:241], v160 offset:4096
	ds_read_b128 v[242:245], v160 offset:6144
	v_lshl_add_u64 v[128:129], v[150:151], 0, s[86:87]
	v_lshl_add_u64 v[130:131], v[148:149], 0, s[86:87]
	v_mfma_f32_16x16x32_bf16 v[60:63], v[214:217], v[246:249], v[60:63]
	v_mfma_f32_16x16x32_bf16 v[56:59], v[218:221], v[246:249], v[56:59]
	v_mfma_f32_16x16x32_bf16 v[52:55], v[222:225], v[246:249], v[52:55]
	v_mfma_f32_16x16x32_bf16 v[48:51], v[226:229], v[246:249], v[48:51]
	s_mov_b64 s[80:81], 0x669b080
	v_lshl_add_u64 v[162:163], v[128:129], 0, s[80:81]
	s_mov_b32 m0, s91
	s_nop 0
	global_load_lds_dwordx4 v[162:163], off
	v_mfma_f32_16x16x32_bf16 v[44:47], v[214:217], v[196:199], v[44:47]
	v_mfma_f32_16x16x32_bf16 v[40:43], v[218:221], v[196:199], v[40:43]
	v_mfma_f32_16x16x32_bf16 v[36:39], v[222:225], v[196:199], v[36:39]
	v_mfma_f32_16x16x32_bf16 v[32:35], v[226:229], v[196:199], v[32:35]
	s_mov_b64 s[80:81], 0x66f3080
	v_lshl_add_u64 v[164:165], v[128:129], 0, s[80:81]
	s_add_i32 m0, s91, 0x2000
	s_nop 0
	global_load_lds_dwordx4 v[164:165], off
	v_mfma_f32_16x16x32_bf16 v[28:31], v[214:217], v[152:155], v[28:31]
	v_mfma_f32_16x16x32_bf16 v[24:27], v[218:221], v[152:155], v[24:27]
	v_mfma_f32_16x16x32_bf16 v[20:23], v[222:225], v[152:155], v[20:23]
	v_mfma_f32_16x16x32_bf16 v[16:19], v[226:229], v[152:155], v[16:19]
	s_mov_b64 s[80:81], 0x674b080
	v_lshl_add_u64 v[162:163], v[128:129], 0, s[80:81]
	s_add_i32 m0, s91, 0x4000
	s_nop 0
	global_load_lds_dwordx4 v[162:163], off
	v_mfma_f32_16x16x32_bf16 v[12:15], v[214:217], v[156:159], v[12:15]
	v_mfma_f32_16x16x32_bf16 v[4:7], v[218:221], v[156:159], v[4:7]
	v_mfma_f32_16x16x32_bf16 v[0:3], v[222:225], v[156:159], v[0:3]
	v_mfma_f32_16x16x32_bf16 v[8:11], v[226:229], v[156:159], v[8:11]
	s_mov_b64 s[80:81], 0x67a3080
	v_lshl_add_u64 v[164:165], v[128:129], 0, s[80:81]
	s_add_i32 m0, s91, 0x6000
	s_nop 0
	global_load_lds_dwordx4 v[164:165], off
	s_waitcnt lgkmcnt(0)
	ds_read_b128 v[214:217], v251 offset:32768
	ds_read_b128 v[218:221], v251 offset:34816
	ds_read_b128 v[222:225], v251 offset:36864
	ds_read_b128 v[226:229], v251 offset:38912
	ds_read_b128 v[246:249], v160 offset:8192
	ds_read_b128 v[196:199], v160 offset:10240
	ds_read_b128 v[152:155], v160 offset:12288
	ds_read_b128 v[156:159], v160 offset:14336
	v_mfma_f32_16x16x32_bf16 v[124:127], v[180:183], v[230:233], v[124:127]
	v_mfma_f32_16x16x32_bf16 v[120:123], v[184:187], v[230:233], v[120:123]
	v_mfma_f32_16x16x32_bf16 v[116:119], v[188:191], v[230:233], v[116:119]
	v_mfma_f32_16x16x32_bf16 v[112:115], v[192:195], v[230:233], v[112:115]
	s_mov_b64 s[80:81], 0x1f52080
	v_lshl_add_u64 v[162:163], v[130:131], 0, s[80:81]
	s_add_i32 m0, s91, 0x8000
	s_nop 0
	global_load_lds_dwordx4 v[162:163], off
	ds_read_b128 v[230:233], v250
	v_mfma_f32_16x16x32_bf16 v[108:111], v[180:183], v[234:237], v[108:111]
	v_mfma_f32_16x16x32_bf16 v[104:107], v[184:187], v[234:237], v[104:107]
	v_mfma_f32_16x16x32_bf16 v[100:103], v[188:191], v[234:237], v[100:103]
	v_mfma_f32_16x16x32_bf16 v[96:99], v[192:195], v[234:237], v[96:99]
	s_mov_b64 s[80:81], 0x1faa080
	v_lshl_add_u64 v[164:165], v[130:131], 0, s[80:81]
	s_add_i32 m0, s91, 0xa000
	s_nop 0
	global_load_lds_dwordx4 v[164:165], off
	ds_read_b128 v[234:237], v250 offset:2048
	v_mfma_f32_16x16x32_bf16 v[92:95], v[180:183], v[238:241], v[92:95]
	v_mfma_f32_16x16x32_bf16 v[88:91], v[184:187], v[238:241], v[88:91]
	v_mfma_f32_16x16x32_bf16 v[84:87], v[188:191], v[238:241], v[84:87]
	v_mfma_f32_16x16x32_bf16 v[80:83], v[192:195], v[238:241], v[80:83]
	s_mov_b64 s[80:81], 0x2002080
	v_lshl_add_u64 v[162:163], v[130:131], 0, s[80:81]
	s_add_i32 m0, s91, 0xc000
	s_nop 0
	global_load_lds_dwordx4 v[162:163], off
	ds_read_b128 v[238:241], v250 offset:4096
	v_mfma_f32_16x16x32_bf16 v[76:79], v[180:183], v[242:245], v[76:79]
	v_mfma_f32_16x16x32_bf16 v[72:75], v[184:187], v[242:245], v[72:75]
	v_mfma_f32_16x16x32_bf16 v[68:71], v[188:191], v[242:245], v[68:71]
	v_mfma_f32_16x16x32_bf16 v[64:67], v[192:195], v[242:245], v[64:67]
	s_mov_b64 s[80:81], 0x205a080
	v_lshl_add_u64 v[164:165], v[130:131], 0, s[80:81]
	s_add_i32 m0, s91, 0xe000
	s_nop 0
	global_load_lds_dwordx4 v[164:165], off
	ds_read_b128 v[242:245], v250 offset:6144
	s_waitcnt lgkmcnt(7)
	v_mfma_f32_16x16x32_bf16 v[60:63], v[180:183], v[246:249], v[60:63]
	v_mfma_f32_16x16x32_bf16 v[56:59], v[184:187], v[246:249], v[56:59]
	v_mfma_f32_16x16x32_bf16 v[52:55], v[188:191], v[246:249], v[52:55]
	v_mfma_f32_16x16x32_bf16 v[48:51], v[192:195], v[246:249], v[48:51]
	ds_read_b128 v[246:249], v250 offset:8192
	s_waitcnt lgkmcnt(7)
	v_mfma_f32_16x16x32_bf16 v[44:47], v[180:183], v[196:199], v[44:47]
	v_mfma_f32_16x16x32_bf16 v[40:43], v[184:187], v[196:199], v[40:43]
	v_mfma_f32_16x16x32_bf16 v[36:39], v[188:191], v[196:199], v[36:39]
	v_mfma_f32_16x16x32_bf16 v[32:35], v[192:195], v[196:199], v[32:35]
	ds_read_b128 v[196:199], v250 offset:10240
	s_waitcnt lgkmcnt(7)
	v_mfma_f32_16x16x32_bf16 v[28:31], v[180:183], v[152:155], v[28:31]
	v_mfma_f32_16x16x32_bf16 v[24:27], v[184:187], v[152:155], v[24:27]
	v_mfma_f32_16x16x32_bf16 v[20:23], v[188:191], v[152:155], v[20:23]
	v_mfma_f32_16x16x32_bf16 v[16:19], v[192:195], v[152:155], v[16:19]
	ds_read_b128 v[152:155], v250 offset:12288
	s_waitcnt lgkmcnt(7)
; __device__ __forceinline__ void gemm_stream256(f32x4 (&acc)[8][4], const Seg& cur, const Seg& nxt, bool has_next, bool first, int& st, unsigned char* lds, int tid) {
;     ...
;     for (int kt = 0; kt < nk; ++kt) {
;         const int idx = kt + 1;
;         const bool incur = idx < nk, doi = incur || has_next;
;         if (!late && doi) { if (incur) issue(apc, bpc, cur.lda, cur.ldb, idx * 64, s0 ^ 1); else issue(apn, bpn, nxt.lda, nxt.ldb, 0, s0 ^ 1); }
;         const unsigned char* As = lds + s0 * STAGE;
;         const unsigned char* Bs = As + 256 * 128;
; #pragma unroll
;         for (int ks = 0; ks < 2; ++ks) {
;             if (ks == 1 && late && doi) { if (incur) issue(apc, bpc, cur.lda, cur.ldb, idx * 64, s0 ^ 1); else issue(apn, bpn, nxt.lda, nxt.ldb, 0, s0 ^ 1); }
;             bf16x8 af[8], bfr[4];
;             const int co = ((ks * 4 + fq) ^ sz) * 16;
; #pragma unroll
;             for (int m = 0; m < 8; ++m) af[m] = *(const bf16x8*)(As + (wr * 128 + m * 16 + fr) * 128 + co);
; #pragma unroll
;             for (int n = 0; n < 4; ++n) bfr[n] = *(const bf16x8*)(Bs + (wc * 64 + n * 16 + fr) * 128 + co);
; #pragma unroll
;             for (int m = 0; m < 8; ++m)
; #pragma unroll
;                 for (int n = 0; n < 4; ++n) acc[m][n] = __builtin_amdgcn_mfma_f32_16x16x32_bf16(bfr[n], af[m], acc[m][n], 0, 0, 0);
;         }
;         asm volatile("s_waitcnt vmcnt(0) lgkmcnt(0)" ::: "memory");
;         __builtin_amdgcn_s_barrier();
;         asm volatile("" ::: "memory");
;         s0 ^= 1;
;     }
	v_mfma_f32_16x16x32_bf16 v[12:15], v[180:183], v[156:159], v[12:15]
	v_mfma_f32_16x16x32_bf16 v[4:7], v[184:187], v[156:159], v[4:7]
	v_mfma_f32_16x16x32_bf16 v[0:3], v[188:191], v[156:159], v[0:3]
	v_mfma_f32_16x16x32_bf16 v[8:11], v[192:195], v[156:159], v[8:11]
	ds_read_b128 v[156:159], v250 offset:14336
	s_waitcnt lgkmcnt(7)
	v_mfma_f32_16x16x32_bf16 v[124:127], v[214:217], v[230:233], v[124:127]
	v_mfma_f32_16x16x32_bf16 v[120:123], v[218:221], v[230:233], v[120:123]
	v_mfma_f32_16x16x32_bf16 v[116:119], v[222:225], v[230:233], v[116:119]
	v_mfma_f32_16x16x32_bf16 v[112:115], v[226:229], v[230:233], v[112:115]
	s_waitcnt lgkmcnt(6)
	v_mfma_f32_16x16x32_bf16 v[108:111], v[214:217], v[234:237], v[108:111]
	v_mfma_f32_16x16x32_bf16 v[104:107], v[218:221], v[234:237], v[104:107]
	v_mfma_f32_16x16x32_bf16 v[100:103], v[222:225], v[234:237], v[100:103]
	v_mfma_f32_16x16x32_bf16 v[96:99], v[226:229], v[234:237], v[96:99]
	s_waitcnt lgkmcnt(5)
	v_mfma_f32_16x16x32_bf16 v[92:95], v[214:217], v[238:241], v[92:95]
	v_mfma_f32_16x16x32_bf16 v[88:91], v[218:221], v[238:241], v[88:91]
	v_mfma_f32_16x16x32_bf16 v[84:87], v[222:225], v[238:241], v[84:87]
	v_mfma_f32_16x16x32_bf16 v[80:83], v[226:229], v[238:241], v[80:83]
	s_waitcnt lgkmcnt(4)
	v_mfma_f32_16x16x32_bf16 v[76:79], v[214:217], v[242:245], v[76:79]
	v_mfma_f32_16x16x32_bf16 v[72:75], v[218:221], v[242:245], v[72:75]
	v_mfma_f32_16x16x32_bf16 v[68:71], v[222:225], v[242:245], v[68:71]
	v_mfma_f32_16x16x32_bf16 v[64:67], v[226:229], v[242:245], v[64:67]
	s_add_u32 s86, s86, 0x80
	s_cmpk_eq_i32 s86, 0x1580
	s_cselect_b32 s86, 0, s86
	s_add_i32 s90, s90, 1
	s_xor_b32 s75, s75, 1
	s_waitcnt vmcnt(0) lgkmcnt(0)
	s_barrier
	s_cmpk_lg_i32 s90, 43
	s_cbranch_scc1 .Lp8_kloop
	s_lshl_b32 s2, s75, 16
	s_xor_b32 s91, s2, 0x10000
	s_add_i32 s91, s71, s91
	v_add3_u32 v179, s2, v174, v178
	v_add3_u32 v160, s2, v174, v177
	v_add3_u32 v251, s2, v175, v178
	v_add3_u32 v250, s2, v175, v177
	ds_read_b128 v[180:183], v179 offset:32768
	ds_read_b128 v[184:187], v179 offset:34816
	ds_read_b128 v[188:191], v179 offset:36864
	ds_read_b128 v[192:195], v179 offset:38912
	ds_read_b128 v[230:233], v160
	ds_read_b128 v[234:237], v160 offset:2048
	ds_read_b128 v[238:241], v160 offset:4096
	ds_read_b128 v[242:245], v160 offset:6144
	v_mfma_f32_16x16x32_bf16 v[60:63], v[214:217], v[246:249], v[60:63]
	v_mfma_f32_16x16x32_bf16 v[56:59], v[218:221], v[246:249], v[56:59]
	v_mfma_f32_16x16x32_bf16 v[52:55], v[222:225], v[246:249], v[52:55]
	v_mfma_f32_16x16x32_bf16 v[48:51], v[226:229], v[246:249], v[48:51]
	v_mfma_f32_16x16x32_bf16 v[44:47], v[214:217], v[196:199], v[44:47]
	v_mfma_f32_16x16x32_bf16 v[40:43], v[218:221], v[196:199], v[40:43]
	v_mfma_f32_16x16x32_bf16 v[36:39], v[222:225], v[196:199], v[36:39]
	v_mfma_f32_16x16x32_bf16 v[32:35], v[226:229], v[196:199], v[32:35]
	v_mfma_f32_16x16x32_bf16 v[28:31], v[214:217], v[152:155], v[28:31]
	v_mfma_f32_16x16x32_bf16 v[24:27], v[218:221], v[152:155], v[24:27]
	v_mfma_f32_16x16x32_bf16 v[20:23], v[222:225], v[152:155], v[20:23]
	v_mfma_f32_16x16x32_bf16 v[16:19], v[226:229], v[152:155], v[16:19]
	v_mfma_f32_16x16x32_bf16 v[12:15], v[214:217], v[156:159], v[12:15]
	v_mfma_f32_16x16x32_bf16 v[4:7], v[218:221], v[156:159], v[4:7]
	v_mfma_f32_16x16x32_bf16 v[0:3], v[222:225], v[156:159], v[0:3]
	v_mfma_f32_16x16x32_bf16 v[8:11], v[226:229], v[156:159], v[8:11]
	s_waitcnt lgkmcnt(0)
	ds_read_b128 v[214:217], v251 offset:32768
	ds_read_b128 v[218:221], v251 offset:34816
	ds_read_b128 v[222:225], v251 offset:36864
	ds_read_b128 v[226:229], v251 offset:38912
	ds_read_b128 v[246:249], v160 offset:8192
	ds_read_b128 v[196:199], v160 offset:10240
	ds_read_b128 v[152:155], v160 offset:12288
	ds_read_b128 v[156:159], v160 offset:14336
	v_mfma_f32_16x16x32_bf16 v[124:127], v[180:183], v[230:233], v[124:127]
	v_mfma_f32_16x16x32_bf16 v[120:123], v[184:187], v[230:233], v[120:123]
	v_mfma_f32_16x16x32_bf16 v[116:119], v[188:191], v[230:233], v[116:119]
	v_mfma_f32_16x16x32_bf16 v[112:115], v[192:195], v[230:233], v[112:115]
	ds_read_b128 v[230:233], v250
	v_mfma_f32_16x16x32_bf16 v[108:111], v[180:183], v[234:237], v[108:111]
	v_mfma_f32_16x16x32_bf16 v[104:107], v[184:187], v[234:237], v[104:107]
	v_mfma_f32_16x16x32_bf16 v[100:103], v[188:191], v[234:237], v[100:103]
	v_mfma_f32_16x16x32_bf16 v[96:99], v[192:195], v[234:237], v[96:99]
	ds_read_b128 v[234:237], v250 offset:2048
	v_mfma_f32_16x16x32_bf16 v[92:95], v[180:183], v[238:241], v[92:95]
	v_mfma_f32_16x16x32_bf16 v[88:91], v[184:187], v[238:241], v[88:91]
	v_mfma_f32_16x16x32_bf16 v[84:87], v[188:191], v[238:241], v[84:87]
	v_mfma_f32_16x16x32_bf16 v[80:83], v[192:195], v[238:241], v[80:83]
	ds_read_b128 v[238:241], v250 offset:4096
	v_mfma_f32_16x16x32_bf16 v[76:79], v[180:183], v[242:245], v[76:79]
	v_mfma_f32_16x16x32_bf16 v[72:75], v[184:187], v[242:245], v[72:75]
	v_mfma_f32_16x16x32_bf16 v[68:71], v[188:191], v[242:245], v[68:71]
	v_mfma_f32_16x16x32_bf16 v[64:67], v[192:195], v[242:245], v[64:67]
	ds_read_b128 v[242:245], v250 offset:6144
	s_waitcnt lgkmcnt(7)
; __device__ __forceinline__ void gemm_stream256(f32x4 (&acc)[8][4], const Seg& cur, const Seg& nxt, bool has_next, bool first, int& st, unsigned char* lds, int tid) {
;     ...
;     for (int kt = 0; kt < nk; ++kt) {
;         const int idx = kt + 1;
;         const bool incur = idx < nk, doi = incur || has_next;
;         if (!late && doi) { if (incur) issue(apc, bpc, cur.lda, cur.ldb, idx * 64, s0 ^ 1); else issue(apn, bpn, nxt.lda, nxt.ldb, 0, s0 ^ 1); }
;         const unsigned char* As = lds + s0 * STAGE;
;         const unsigned char* Bs = As + 256 * 128;
; #pragma unroll
;         for (int ks = 0; ks < 2; ++ks) {
;             if (ks == 1 && late && doi) { if (incur) issue(apc, bpc, cur.lda, cur.ldb, idx * 64, s0 ^ 1); else issue(apn, bpn, nxt.lda, nxt.ldb, 0, s0 ^ 1); }
;             bf16x8 af[8], bfr[4];
;             const int co = ((ks * 4 + fq) ^ sz) * 16;
; #pragma unroll
;             for (int m = 0; m < 8; ++m) af[m] = *(const bf16x8*)(As + (wr * 128 + m * 16 + fr) * 128 + co);
; #pragma unroll
;             for (int n = 0; n < 4; ++n) bfr[n] = *(const bf16x8*)(Bs + (wc * 64 + n * 16 + fr) * 128 + co);
; #pragma unroll
;             for (int m = 0; m < 8; ++m)
; #pragma unroll
;                 for (int n = 0; n < 4; ++n) acc[m][n] = __builtin_amdgcn_mfma_f32_16x16x32_bf16(bfr[n], af[m], acc[m][n], 0, 0, 0);
;         }
;         asm volatile("s_waitcnt vmcnt(0) lgkmcnt(0)" ::: "memory");
;         __builtin_amdgcn_s_barrier();
;         asm volatile("" ::: "memory");
;         s0 ^= 1;
;     }
	v_mfma_f32_16x16x32_bf16 v[60:63], v[180:183], v[246:249], v[60:63]
	v_mfma_f32_16x16x32_bf16 v[56:59], v[184:187], v[246:249], v[56:59]
	v_mfma_f32_16x16x32_bf16 v[52:55], v[188:191], v[246:249], v[52:55]
	v_mfma_f32_16x16x32_bf16 v[48:51], v[192:195], v[246:249], v[48:51]
	ds_read_b128 v[246:249], v250 offset:8192
	s_waitcnt lgkmcnt(7)
	v_mfma_f32_16x16x32_bf16 v[44:47], v[180:183], v[196:199], v[44:47]
	v_mfma_f32_16x16x32_bf16 v[40:43], v[184:187], v[196:199], v[40:43]
	v_mfma_f32_16x16x32_bf16 v[36:39], v[188:191], v[196:199], v[36:39]
	v_mfma_f32_16x16x32_bf16 v[32:35], v[192:195], v[196:199], v[32:35]
	ds_read_b128 v[196:199], v250 offset:10240
	s_waitcnt lgkmcnt(7)
	v_mfma_f32_16x16x32_bf16 v[28:31], v[180:183], v[152:155], v[28:31]
	v_mfma_f32_16x16x32_bf16 v[24:27], v[184:187], v[152:155], v[24:27]
	v_mfma_f32_16x16x32_bf16 v[20:23], v[188:191], v[152:155], v[20:23]
	v_mfma_f32_16x16x32_bf16 v[16:19], v[192:195], v[152:155], v[16:19]
	ds_read_b128 v[152:155], v250 offset:12288
	s_waitcnt lgkmcnt(7)
	v_mfma_f32_16x16x32_bf16 v[12:15], v[180:183], v[156:159], v[12:15]
	v_mfma_f32_16x16x32_bf16 v[4:7], v[184:187], v[156:159], v[4:7]
	v_mfma_f32_16x16x32_bf16 v[0:3], v[188:191], v[156:159], v[0:3]
	v_mfma_f32_16x16x32_bf16 v[8:11], v[192:195], v[156:159], v[8:11]
	ds_read_b128 v[156:159], v250 offset:14336
	s_waitcnt lgkmcnt(7)
	v_mfma_f32_16x16x32_bf16 v[124:127], v[214:217], v[230:233], v[124:127]
	v_mfma_f32_16x16x32_bf16 v[120:123], v[218:221], v[230:233], v[120:123]
	v_mfma_f32_16x16x32_bf16 v[116:119], v[222:225], v[230:233], v[116:119]
	v_mfma_f32_16x16x32_bf16 v[112:115], v[226:229], v[230:233], v[112:115]
	s_waitcnt lgkmcnt(6)
	v_mfma_f32_16x16x32_bf16 v[108:111], v[214:217], v[234:237], v[108:111]
	v_mfma_f32_16x16x32_bf16 v[104:107], v[218:221], v[234:237], v[104:107]
	v_mfma_f32_16x16x32_bf16 v[100:103], v[222:225], v[234:237], v[100:103]
	v_mfma_f32_16x16x32_bf16 v[96:99], v[226:229], v[234:237], v[96:99]
	s_waitcnt lgkmcnt(5)
	v_mfma_f32_16x16x32_bf16 v[92:95], v[214:217], v[238:241], v[92:95]
	v_mfma_f32_16x16x32_bf16 v[88:91], v[218:221], v[238:241], v[88:91]
	v_mfma_f32_16x16x32_bf16 v[84:87], v[222:225], v[238:241], v[84:87]
	v_mfma_f32_16x16x32_bf16 v[80:83], v[226:229], v[238:241], v[80:83]
	s_waitcnt lgkmcnt(4)
	v_mfma_f32_16x16x32_bf16 v[76:79], v[214:217], v[242:245], v[76:79]
	v_mfma_f32_16x16x32_bf16 v[72:75], v[218:221], v[242:245], v[72:75]
	v_mfma_f32_16x16x32_bf16 v[68:71], v[222:225], v[242:245], v[68:71]
	v_mfma_f32_16x16x32_bf16 v[64:67], v[226:229], v[242:245], v[64:67]
	s_waitcnt lgkmcnt(3)
	v_mfma_f32_16x16x32_bf16 v[60:63], v[214:217], v[246:249], v[60:63]
	v_mfma_f32_16x16x32_bf16 v[56:59], v[218:221], v[246:249], v[56:59]
	v_mfma_f32_16x16x32_bf16 v[52:55], v[222:225], v[246:249], v[52:55]
	v_mfma_f32_16x16x32_bf16 v[48:51], v[226:229], v[246:249], v[48:51]
	s_waitcnt lgkmcnt(2)
	v_mfma_f32_16x16x32_bf16 v[44:47], v[214:217], v[196:199], v[44:47]
	v_mfma_f32_16x16x32_bf16 v[40:43], v[218:221], v[196:199], v[40:43]
	v_mfma_f32_16x16x32_bf16 v[36:39], v[222:225], v[196:199], v[36:39]
	v_mfma_f32_16x16x32_bf16 v[32:35], v[226:229], v[196:199], v[32:35]
	s_waitcnt lgkmcnt(1)
	v_mfma_f32_16x16x32_bf16 v[28:31], v[214:217], v[152:155], v[28:31]
	v_mfma_f32_16x16x32_bf16 v[24:27], v[218:221], v[152:155], v[24:27]
	v_mfma_f32_16x16x32_bf16 v[20:23], v[222:225], v[152:155], v[20:23]
	v_mfma_f32_16x16x32_bf16 v[16:19], v[226:229], v[152:155], v[16:19]
	s_waitcnt lgkmcnt(0)
	v_mfma_f32_16x16x32_bf16 v[12:15], v[214:217], v[156:159], v[12:15]
	v_mfma_f32_16x16x32_bf16 v[4:7], v[218:221], v[156:159], v[4:7]
	v_mfma_f32_16x16x32_bf16 v[0:3], v[222:225], v[156:159], v[0:3]
	v_mfma_f32_16x16x32_bf16 v[8:11], v[226:229], v[156:159], v[8:11]
	s_waitcnt vmcnt(0) lgkmcnt(0)
	s_barrier
	s_branch .LBB0_1074
